# rwkv chunk scans: per-chunk global loads prefetched one chunk ahead
# speedup vs baseline: 1.0194x; 1.0194x over previous
; template <bool PA> ...
;     ...
;         const int g = item % G, strm = item / G; const int p0 = g == 0 ? 0 : 1 + 32 * g, p1 = 33 + 32 * g;
;         const bool haveT = !PA;
;         const int d = strm & 1, head = (strm >> 1) & 15, sq = strm >> 5; const int seqbase = sq * 8256; const int hc8 = head * 64 + c8;
;         bf16* Op = d ? OBb : OFb;
;         const float* w0 = a->in[15] + d * 1024; const float* w2 = a->in[17] + (size_t)d * 64 * 1024; const float* a0 = a->in[18] + d * 1024; const float* a2 = a->in[20] + (size_t)d * 64 * 1024;
;         __syncthreads();
;         if (tid < 320) { const int wch = tid >> 6, cc = tid & 63; const float* src = wch == 0 ? w0 : (wch == 1 ? a0 : (wch == 2 ? a->in[23] : (wch == 3 ? a->in[24] : a->in[25]))); cst[tid] = src[head * 64 + cc]; }
;         for (int i = tid; i < 4096; i += 512) { const int l = i >> 6, cc = i & 63; w2T[cc * 72 + l] = (bf16)f2bf(w2[(size_t)l * 1024 + head * 64 + cc]); a2T[cc * 72 + l] = (bf16)f2bf(a2[(size_t)l * 1024 + head * 64 + cc]); }
;         f32x4_t Sacc[2], S2acc[2]; Sacc[0] = (f32x4_t){0.f, 0.f, 0.f, 0.f}; Sacc[1] = Sacc[0];
; #pragma unroll
;         for (int i = 0; i < 2; ++i)
; #pragma unroll
;             for (int e = 0; e < 4; ++e) S2acc[i][e] = (16 * mt + 4 * kq + e == 16 * (ntb + i) + r16) ? 1.f : 0.f;
;         __syncthreads();
;         if (!PA) {
;             for (int gg = 0; gg < g; ++gg) {
;                 const float* Psi = segm + (size_t)(strm * G + gg) * 8192; const float* Phi = Psi + 4096;
;                 { const f32x4_t q0 = *(const f32x4_t*)(Phi + j * 64 + c8), q1 = *(const f32x4_t*)(Phi + j * 64 + c8 + 4);
; #pragma unroll
;                   for (int e = 0; e < 4; ++e) { MAT(1)[(c8 + e) * 72 + j] = (bf16)f2bf(q0[e]); MAT(1)[(c8 + 4 + e) * 72 + j] = (bf16)f2bf(q1[e]); } }
;                 st_rm(MAT(0), Sacc, mt, ntb, r16, kq);
;                 __syncthreads();
; #pragma unroll
;                 for (int i = 0; i < 2; ++i)
; #pragma unroll
;                     for (int e = 0; e < 4; ++e) Sacc[i][e] = Psi[(16 * mt + 4 * kq + e) * 64 + 16 * (ntb + i) + r16];
;                 mm2(Sacc, MAT(0), MAT(1), mt, ntb, r16, kq);
;                 __syncthreads();
;             }
;         }
;         for (int p = p0; p < p1; ++p) {
;             const int cidx = d ? nch - 1 - p : p; const int cbase = seqbase + cidx * 64;
.LBB0_150:
	s_lshl_b32 s13, s0, 5
	s_or_b32 s1, s13, 1
	s_cmp_lg_u32 s0, 0
	s_cselect_b32 s12, s1, 0
	s_add_i32 s13, s13, 33
	s_cmp_ge_i32 s12, s13
	s_cbranch_scc1 .LBB0_128
	s_lshr_b32 s0, s24, 5
	s_cmp_eq_u32 s9, 0
	s_cselect_b64 vcc, -1, 0
	s_mul_i32 s18, s0, 0x2040
	v_or_b32_e32 v0, s15, v85
	s_and_b64 s[0:1], vcc, exec
	v_readlane_b32 s20, v255, 30
	s_mov_b32 s0, 0x7980000
	v_lshlrev_b32_e32 v0, 1, v0
	v_readlane_b32 s21, v255, 31
	s_cselect_b32 s0, 0x5900000, s0
	v_cndmask_b32_e32 v10, v90, v84, vcc
	v_lshl_add_u64 v[70:71], s[20:21], 0, v[0:1]
	v_readlane_b32 s20, v255, 34
	s_add_u32 s0, s6, s0
	v_readlane_b32 s21, v255, 35
	s_addc_u32 s1, s7, 0
	v_add_u32_e32 v130, s18, v10
	s_mul_hi_i32 s15, s24, s91
	s_mul_i32 s18, s24, s91
	s_lshl_b32 s24, s9, 7
	v_lshl_add_u64 v[72:73], s[20:21], 0, v[0:1]
	v_readlane_b32 s20, v255, 28
	v_lshl_add_u64 v[66:67], v[42:43], 0, s[24:25]
	v_lshl_add_u64 v[68:69], v[44:45], 0, s[24:25]
	v_readlane_b32 s21, v255, 29
	s_mul_i32 s24, s9, 0x4100
	s_lshl_b32 s9, s11, 2
	v_readlane_b32 s11, v255, 14
	v_lshl_add_u64 v[74:75], s[20:21], 0, v[0:1]
	s_add_u32 s20, s11, s9
	v_readlane_b32 s9, v255, 15
	s_addc_u32 s21, s9, 0
	v_lshl_add_u64 v[76:77], s[0:1], 0, v[0:1]
	s_ashr_i32 s0, s12, 31
	s_add_u32 s1, s18, s12
	s_addc_u32 s0, s15, s0
	s_mul_i32 s9, s0, 0x1200
	v_mad_u64_u32 v[78:79], s[0:1], s1, v199, v[64:65]
	v_readlane_b32 s0, v255, 16
	v_add_u32_e32 v79, s9, v79
	s_sub_i32 s18, s0, s12
	v_mov_b32_e32 v228, 0
	v_mov_b32_e32 v229, 0
	v_mov_b32_e32 v230, 0
	v_mov_b32_e32 v231, 0
	s_and_saveexec_b64 s[0:1], s[36:37]
	global_load_dwordx4 v[228:231], v[78:79], off
	s_or_b64 exec, exec, s[0:1]
	v_lshl_add_u64 v[78:79], v[78:79], 0, s[34:35]
	s_and_b64 s[0:1], vcc, exec
	s_cselect_b32 s0, s12, s18
	v_lshl_add_u32 v226, s0, 6, v130
	v_ashrrev_i32_e32 v227, 31, v226
	v_lshlrev_b64 v[224:225], 8, v[226:227]
	v_lshl_add_u64 v[222:223], v[66:67], 0, v[224:225]
	global_load_dwordx4 v[232:235], v[222:223], off
	v_lshl_add_u64 v[222:223], v[68:69], 0, v[224:225]
	global_load_dwordx4 v[236:239], v[222:223], off
	v_lshlrev_b64 v[224:225], 11, v[226:227]
	v_lshl_add_u64 v[222:223], v[70:71], 0, v[224:225]
	global_load_dwordx4 v[240:243], v[222:223], off
	v_lshl_add_u64 v[222:223], v[72:73], 0, v[224:225]
	global_load_dwordx4 v[244:247], v[222:223], off
	v_lshl_add_u64 v[222:223], v[74:75], 0, v[224:225]
	global_load_dwordx4 v[248:251], v[222:223], off
	s_waitcnt vmcnt(0)
	s_branch .LBB0_153
.LBB0_152:
	s_or_b64 exec, exec, s[0:1]
	v_lshlrev_b64 v[34:35], 10, v[80:81]
	v_add_f32_e32 v80, v149, v150
	v_max_f32_e32 v80, 0x179abe15, v80
	v_sub_f32_e32 v25, v33, v25
	v_rsq_f32_e32 v80, v80
	v_mul_f32_e32 v25, 0x3fb8aa3b, v25
	v_sub_f32_e32 v24, v32, v24
	v_exp_f32_e32 v25, v25
	v_mul_f32_e32 v24, 0x3fb8aa3b, v24
	v_sub_f32_e32 v23, v31, v23
	v_exp_f32_e32 v24, v24
	v_mul_f32_e32 v23, 0x3fb8aa3b, v23
	v_exp_f32_e32 v23, v23
	v_mul_f32_e32 v81, v145, v80
	v_mul_f32_e32 v145, 0xbfb8aa3b, v33
	v_mul_f32_e32 v25, v81, v25
	v_mul_f32_e64 v33, v81, -v40
	v_mul_f32_e32 v81, v144, v80
	v_mul_f32_e32 v40, v164, v143
	v_mul_f32_e32 v143, 0xbfb8aa3b, v32
	v_mul_f32_e32 v24, v81, v24
	v_mul_f32_e64 v32, v81, -v39
	v_mul_f32_e32 v81, v142, v80
	v_sub_f32_e32 v22, v30, v22
	v_mul_f32_e32 v39, v161, v141
	v_mul_f32_e32 v141, 0xbfb8aa3b, v31
	v_mul_f32_e32 v23, v81, v23
	v_mul_f32_e64 v31, v81, -v38
	v_mul_f32_e32 v81, v158, v139
	v_mul_f32_e32 v139, v140, v80
	v_mul_f32_e32 v140, 0xbfb8aa3b, v30
	v_mul_f32_e32 v22, 0x3fb8aa3b, v22
	v_exp_f32_e32 v140, v140
	v_exp_f32_e32 v22, v22
	v_mul_f32_e64 v30, v139, -v163
	v_sub_f32_e32 v21, v29, v21
	v_mul_f32_e32 v30, v30, v140
	v_mul_f32_e32 v22, v139, v22
	v_mul_f32_e32 v139, v165, v140
	v_mul_f32_e32 v140, 0xbfb8aa3b, v29
	v_mul_f32_e32 v21, 0x3fb8aa3b, v21
	v_exp_f32_e32 v140, v140
	v_exp_f32_e32 v21, v21
	v_mul_f32_e32 v138, v138, v80
	v_mul_f32_e64 v29, v138, -v159
	v_sub_f32_e32 v20, v28, v20
	v_mul_f32_e32 v21, v138, v21
	v_mul_f32_e32 v29, v29, v140
	v_mul_f32_e32 v138, v160, v140
	v_mul_f32_e32 v140, 0xbfb8aa3b, v28
	v_mul_f32_e32 v20, 0x3fb8aa3b, v20
	v_exp_f32_e32 v140, v140
	v_exp_f32_e32 v20, v20
	v_mul_f32_e32 v136, v136, v80
	v_sub_f32_e32 v19, v27, v19
	v_sub_f32_e32 v18, v26, v18
	v_mul_f32_e64 v28, v136, -v155
	v_mul_f32_e32 v19, 0x3fb8aa3b, v19
	v_mul_f32_e32 v18, 0x3fb8aa3b, v18
	v_mul_f32_e32 v20, v136, v20
	v_mul_f32_e32 v28, v28, v140
	v_mul_f32_e32 v136, v156, v140
	v_mul_f32_e32 v134, v134, v80
	v_mul_f32_e32 v140, 0xbfb8aa3b, v27
	v_exp_f32_e32 v19, v19
	v_mul_f32_e32 v80, v132, v80
	v_mul_f32_e32 v132, 0xbfb8aa3b, v26
	v_exp_f32_e32 v18, v18
	v_exp_f32_e32 v145, v145
	v_exp_f32_e32 v143, v143
	v_exp_f32_e32 v141, v141
	v_exp_f32_e32 v140, v140
	v_exp_f32_e32 v132, v132
	v_mul_f32_e32 v19, v134, v19
	v_mul_f32_e64 v27, v134, -v152
	v_mul_f32_e32 v18, v80, v18
	v_mul_f32_e64 v26, v80, -v148
	v_mul_f32_e32 v33, v33, v145
	v_mul_f32_e32 v37, v37, v145
	v_mul_f32_e32 v32, v32, v143
	v_mul_f32_e32 v36, v36, v143
	v_mul_f32_e32 v31, v31, v141
	v_mul_f32_e32 v38, v162, v141
	v_mul_f32_e32 v137, v157, v137
	v_mul_f32_e32 v135, v154, v135
	v_mul_f32_e32 v133, v147, v133
	v_mul_f32_e32 v27, v27, v140
	v_mul_f32_e32 v134, v153, v140
	v_mul_f32_e32 v131, v146, v131
	v_mul_f32_e32 v26, v26, v132
	v_mul_f32_e32 v80, v151, v132
	v_mul_f32_e32 v0, v41, v0
	v_cvt_pk_bf16_f32 v18, v18, v19
	v_cvt_pk_bf16_f32 v19, v20, v21
	v_cvt_pk_bf16_f32 v20, v22, v23
	v_cvt_pk_bf16_f32 v21, v24, v25
	ds_write_b128 v91, v[18:21]
	v_cvt_pk_bf16_f32 v18, v26, v27
	v_cvt_pk_bf16_f32 v19, v28, v29
	v_cvt_pk_bf16_f32 v20, v30, v31
	v_cvt_pk_bf16_f32 v21, v32, v33
	v_cvt_pk_bf16_f32 v22, v80, v134
; template <bool PA> ...
;     ...
;                 w.x = pk2(ah[0], ah[1]); w.y = pk2(ah[2], ah[3]); w.z = pk2(ah[4], ah[5]); w.w = pk2(ah[6], ah[7]); *(u32x4_t*)(MAT(0) + j * 72 + c8) = w;
;                 u32x4_t wb, wk;
;                 wb.x = pk2(bh[0], bh[1]); wb.y = pk2(bh[2], bh[3]); wb.z = pk2(bh[4], bh[5]); wb.w = pk2(bh[6], bh[7]); *(u32x4_t*)(MAT(1) + j * 72 + c8) = wb;
;                 wk.x = pk2(kh[0], kh[1]); wk.y = pk2(kh[2], kh[3]); wk.z = pk2(kh[4], kh[5]); wk.w = pk2(kh[6], kh[7]); *(u32x4_t*)(MAT(2) + j * 72 + c8) = wk;
;                 w.x = pk2(rh[0], rh[1]); w.y = pk2(rh[2], rh[3]); w.z = pk2(rh[4], rh[5]); w.w = pk2(rh[6], rh[7]); *(u32x4_t*)(MAT(3) + j * 72 + c8) = w;
;                 { const unsigned wba[4] = {wb.x, wb.y, wb.z, wb.w}, wka[4] = {wk.x, wk.y, wk.z, wk.w}, wva[4] = {vraw.x, vraw.y, vraw.z, vraw.w};
; #pragma unroll
;                   for (int q = 0; q < 4; ++q) { bf16* d4 = MAT(4) + (c8 + 2 * q) * 72 + j; bf16* d5 = MAT(5) + (c8 + 2 * q) * 72 + j; bf16* d6 = MAT(6) + (c8 + 2 * q) * 72 + j;
;                       d4[0] = (bf16)(wba[q] & 0xffffu); d4[72] = (bf16)(wba[q] >> 16); d5[0] = (bf16)(wka[q] & 0xffffu); d5[72] = (bf16)(wka[q] >> 16); d6[0] = (bf16)(wva[q] & 0xffffu); d6[72] = (bf16)(wva[q] >> 16); } }
;                 if (haveT) *(u32x4_t*)(MAT(9) + j * 72 + c8) = tld;
;                 st_rm(MAT(7), Sacc, mt, ntb, r16, kq);
;                 if (PA) st_rm(MAT(12), S2acc, mt, ntb, r16, kq);
;             }
;             __syncthreads();
;             f32x4_t Pacc[2], Tacc[2], Xacc[2], Yacc[2], tmp[2];
;             const f32x4_t z4 = (f32x4_t){0.f, 0.f, 0.f, 0.f};
;             Tacc[0] = z4; Tacc[1] = z4;
;             if (!haveT) {
;             Pacc[0] = z4; Pacc[1] = z4; mm2(Pacc, MAT(0), MAT(1), mt, ntb, r16, kq);
; #pragma unroll
;             for (int i = 0; i < 2; ++i)
; #pragma unroll
;                 for (int e = 0; e < 4; ++e) { const int t = 16 * mt + 4 * kq + e, s = 16 * (ntb + i) + r16; Pacc[i][e] = (s < t) ? Pacc[i][e] : 0.f; Tacc[i][e] = Pacc[i][e] + ((s == t) ? 1.f : 0.f); }
;             st_rm(MAT(8), Pacc, mt, ntb, r16, kq); st_tr(MAT(9), Pacc, mt, ntb, r16, kq);
;             }
;             tmp[0] = z4; tmp[1] = z4; mm2(tmp, MAT(0), MAT(2), mt, ntb, r16, kq);
; #pragma unroll
;             for (int i = 0; i < 2; ++i)
; #pragma unroll
	v_cvt_pk_bf16_f32 v23, v136, v138
	v_cvt_pk_bf16_f32 v24, v139, v38
	v_cvt_pk_bf16_f32 v25, v36, v37
	v_cvt_pk_bf16_f32 v26, v0, v131
	v_cvt_pk_bf16_f32 v27, v133, v135
	v_cvt_pk_bf16_f32 v28, v137, v81
	v_cvt_pk_bf16_f32 v29, v39, v40
	ds_write_b128 v91, v[18:21] offset:9216
	ds_write_b128 v91, v[22:25] offset:18432
	ds_write_b128 v91, v[26:29] offset:27648
	ds_write_b16 v117, v18 offset:36864
	ds_write_b16_d16_hi v117, v18 offset:37008
	ds_write_b16 v117, v22 offset:46080
	ds_write_b16_d16_hi v117, v22 offset:46224
	s_nop 0
	ds_write_b16 v117, v14 offset:55296
	ds_write_b16_d16_hi v117, v14 offset:55440
	ds_write_b16 v117, v19 offset:37152
	ds_write_b16_d16_hi v117, v19 offset:37296
	ds_write_b16 v117, v23 offset:46368
	ds_write_b16_d16_hi v117, v23 offset:46512
	ds_write_b16 v117, v15 offset:55584
	ds_write_b16_d16_hi v117, v15 offset:55728
	ds_write_b16 v117, v20 offset:37440
	ds_write_b16_d16_hi v117, v20 offset:37584
	ds_write_b16 v117, v24 offset:46656
	ds_write_b16_d16_hi v117, v24 offset:46800
	ds_write_b16 v117, v16 offset:55872
	ds_write_b16_d16_hi v117, v16 offset:56016
	ds_write_b16 v117, v21 offset:37728
	ds_write_b16_d16_hi v117, v21 offset:37872
	ds_write_b16 v117, v25 offset:46944
	ds_write_b16_d16_hi v117, v25 offset:47088
	ds_write_b16 v117, v17 offset:56160
	ds_write_b16_d16_hi v117, v17 offset:56304
	ds_write_b128 v101, v[10:13]
	v_cvt_pk_bf16_f32 v0, v6, v7
	v_cvt_pk_bf16_f32 v10, v8, v9
	ds_write_b16 v87, v0 offset:64512
	ds_write_b16_d16_hi v87, v0 offset:64656
	ds_write_b16 v87, v10 offset:64800
	ds_write_b16_d16_hi v87, v10 offset:64944
	v_cvt_pk_bf16_f32 v0, v2, v3
	v_cvt_pk_bf16_f32 v10, v4, v5
	ds_write_b16 v87, v0 offset:64544
	ds_write_b16_d16_hi v87, v0 offset:64688
	ds_write_b16 v87, v10 offset:64832
	ds_write_b16_d16_hi v87, v10 offset:64976
	s_waitcnt lgkmcnt(0)
	s_barrier
	ds_read_b128 v[10:13], v92
	ds_read_b128 v[14:17], v89 offset:18432
	ds_read_b128 v[18:21], v89 offset:20736
	s_waitcnt lgkmcnt(1)
	v_mfma_f32_16x16x32_bf16 v[14:17], v[10:13], v[14:17], 0
	s_add_i32 s12, s12, 1
	s_add_i32 s18, s18, -1
	v_lshl_add_u64 v[78:79], v[78:79], 0, s[34:35]
	s_waitcnt lgkmcnt(0)
	v_mfma_f32_16x16x32_bf16 v[10:13], v[10:13], v[18:21], 0
	ds_read_b128 v[18:21], v92 offset:64
	ds_read_b128 v[22:25], v89 offset:18496
	s_cmp_ge_i32 s12, s13
	s_waitcnt lgkmcnt(0)
	v_mfma_f32_16x16x32_bf16 v[14:17], v[18:21], v[22:25], v[14:17]
	ds_read_b128 v[22:25], v89 offset:20800
	s_waitcnt lgkmcnt(0)
	v_mfma_f32_16x16x32_bf16 v[10:13], v[18:21], v[22:25], v[10:13]
	s_nop 4
	v_cndmask_b32_e64 v0, 0, v14, s[62:63]
	v_cndmask_b32_e64 v14, v15, 0, s[64:65]
	v_cndmask_b32_e64 v15, 0, v16, s[66:67]
	v_cndmask_b32_e64 v16, 0, v17, s[68:69]
	v_cndmask_b32_e64 v10, 0, v10, s[70:71]
	v_cndmask_b32_e64 v11, v11, 0, s[72:73]
	v_cvt_pk_bf16_f32 v0, v0, v14
	v_cndmask_b32_e64 v12, 0, v12, s[74:75]
	v_cndmask_b32_e64 v13, 0, v13, s[76:77]
	v_cvt_pk_bf16_f32 v14, v15, v16
	ds_write_b16 v102, v0
	ds_write_b16_d16_hi v102, v0 offset:144
	ds_write_b16 v102, v14 offset:288
	ds_write_b16_d16_hi v102, v14 offset:432
	v_cvt_pk_bf16_f32 v0, v10, v11
	v_cvt_pk_bf16_f32 v10, v12, v13
	ds_write_b16 v102, v0 offset:32
	ds_write_b16_d16_hi v102, v0 offset:176
	ds_write_b16 v102, v10 offset:320
	ds_write_b16_d16_hi v102, v10 offset:464
	ds_read_b128 v[10:13], v92 offset:27648
	ds_read_b128 v[14:17], v89 offset:9216
	ds_read_b128 v[18:21], v89 offset:11520
	s_waitcnt lgkmcnt(1)
	v_mfma_f32_16x16x32_bf16 v[14:17], v[10:13], v[14:17], 0
	s_waitcnt lgkmcnt(0)
	v_mfma_f32_16x16x32_bf16 v[10:13], v[10:13], v[18:21], 0
	ds_read_b128 v[18:21], v92 offset:27712
	ds_read_b128 v[22:25], v89 offset:9280
	s_waitcnt lgkmcnt(0)
	v_mfma_f32_16x16x32_bf16 v[14:17], v[18:21], v[22:25], v[14:17]
	ds_read_b128 v[22:25], v89 offset:11584
	s_waitcnt lgkmcnt(0)
	v_mfma_f32_16x16x32_bf16 v[10:13], v[18:21], v[22:25], v[10:13]
	s_nop 4
	v_cndmask_b32_e64 v0, v14, 0, s[64:65]
	v_cndmask_b32_e64 v14, v15, 0, s[78:79]
	v_cndmask_b32_e64 v15, v16, 0, s[80:81]
	v_cndmask_b32_e64 v16, v17, 0, s[82:83]
	v_cndmask_b32_e64 v10, v10, 0, s[72:73]
	v_cndmask_b32_e64 v11, v11, 0, s[84:85]
	v_cvt_pk_bf16_f32 v0, v0, v14
	v_cndmask_b32_e64 v12, v12, 0, s[86:87]
	v_cndmask_b32_e64 v13, v13, 0, s[88:89]
	v_cvt_pk_bf16_f32 v14, v15, v16
	ds_write_b16 v103, v0
	ds_write_b16_d16_hi v103, v0 offset:144
	ds_write_b16 v103, v14 offset:288
	ds_write_b16_d16_hi v103, v14 offset:432
	v_cvt_pk_bf16_f32 v0, v10, v11
	v_cvt_pk_bf16_f32 v10, v12, v13
	ds_write_b16 v103, v0 offset:32
	ds_write_b16_d16_hi v103, v0 offset:176
	ds_write_b16 v103, v10 offset:320
	ds_write_b16_d16_hi v103, v10 offset:464
	ds_read_b128 v[10:13], v92 offset:27648
	ds_read_b128 v[14:17], v89 offset:18432
	ds_read_b128 v[18:21], v89 offset:20736
	s_waitcnt lgkmcnt(1)
	v_mfma_f32_16x16x32_bf16 v[14:17], v[10:13], v[14:17], 0
	s_waitcnt lgkmcnt(0)
	v_mfma_f32_16x16x32_bf16 v[10:13], v[10:13], v[18:21], 0
	ds_read_b128 v[18:21], v92 offset:27712
	ds_read_b128 v[22:25], v89 offset:18496
	s_waitcnt lgkmcnt(0)
	v_mfma_f32_16x16x32_bf16 v[14:17], v[18:21], v[22:25], v[14:17]
	ds_read_b128 v[22:25], v89 offset:20800
	s_waitcnt lgkmcnt(0)
	v_mfma_f32_16x16x32_bf16 v[10:13], v[18:21], v[22:25], v[10:13]
	s_nop 4
	v_cndmask_b32_e64 v0, v14, 0, s[64:65]
	v_cndmask_b32_e64 v14, v15, 0, s[78:79]
	v_cndmask_b32_e64 v15, v16, 0, s[80:81]
	v_cndmask_b32_e64 v16, v17, 0, s[82:83]
	v_cndmask_b32_e64 v10, v10, 0, s[72:73]
	v_cndmask_b32_e64 v11, v11, 0, s[84:85]
	v_cvt_pk_bf16_f32 v0, v0, v14
	v_cndmask_b32_e64 v12, v12, 0, s[86:87]
	v_cndmask_b32_e64 v13, v13, 0, s[88:89]
	v_cvt_pk_bf16_f32 v14, v15, v16
	ds_write_b16 v104, v0
	ds_write_b16_d16_hi v104, v0 offset:144
	ds_write_b16 v104, v14 offset:288
	ds_write_b16_d16_hi v104, v14 offset:432
	v_cvt_pk_bf16_f32 v0, v10, v11
	v_cvt_pk_bf16_f32 v10, v12, v13
	ds_write_b16 v104, v0 offset:32
	ds_write_b16_d16_hi v104, v0 offset:176
	ds_write_b16 v104, v10 offset:320
	ds_write_b16_d16_hi v104, v10 offset:464
	ds_read_b128 v[10:13], v92
	ds_read_b128 v[14:17], v89 offset:64512
	ds_read_b128 v[22:25], v105
	ds_read_b128 v[26:29], v92 offset:64
	ds_read_b128 v[30:33], v89 offset:64576
	ds_read_b128 v[36:39], v106
	s_waitcnt lgkmcnt(4)
	v_mfma_f32_16x16x32_bf16 v[18:21], v[10:13], v[14:17], 0
	s_waitcnt lgkmcnt(3)
	v_mfma_f32_16x16x32_bf16 v[10:13], v[10:13], v[22:25], 0
	s_waitcnt lgkmcnt(1)
	v_mfma_f32_16x16x32_bf16 v[18:21], v[26:29], v[30:33], v[18:21]
	s_waitcnt lgkmcnt(0)
	v_mfma_f32_16x16x32_bf16 v[10:13], v[26:29], v[36:39], v[10:13]
	ds_read_b128 v[26:29], v92 offset:27648
	s_waitcnt lgkmcnt(0)
	v_mfma_f32_16x16x32_bf16 v[14:17], v[26:29], v[14:17], 0
	v_mfma_f32_16x16x32_bf16 v[22:25], v[26:29], v[22:25], 0
	ds_read_b128 v[26:29], v92 offset:27712
	s_waitcnt lgkmcnt(0)
	s_barrier
; template <bool PA> ...
;     ...
;             const bf16* Tm = haveT ? MAT(9) : MAT(3);
;             mm2(Xacc, MAT(10), MAT(6), mt, ntb, r16, kq);
;             st_tr(MAT(7), Xacc, mt, ntb, r16, kq);
;             if (PA) st_tr(MAT(11), X2acc, mt, ntb, r16, kq);
;             __syncthreads();
;             tmp[0] = z4; tmp[1] = z4; mm2(tmp, Tm, MAT(7), mt, ntb, r16, kq);
;             st_tr(MAT(8), tmp, mt, ntb, r16, kq);
;             if (PA) { tmp[0] = z4; tmp[1] = z4; mm2(tmp, MAT(3), MAT(11), mt, ntb, r16, kq); st_tr(MAT(12), tmp, mt, ntb, r16, kq); }
;             __syncthreads();
;             if (!PA) { mm2(Yacc, MAT(11), MAT(8), mt, ntb, r16, kq); mm2(Yacc, MAT(12), MAT(6), mt, ntb, r16, kq);
;             st_rm(MAT(7), Yacc, mt, ntb, r16, kq); }
;             if (PA) mm2(S2acc, MAT(12), MAT(4), mt, ntb, r16, kq);
;             mm2(Sacc, MAT(8), MAT(4), mt, ntb, r16, kq); mm2(Sacc, MAT(6), MAT(5), mt, ntb, r16, kq);
; #pragma unroll
;             for (int i = 0; i < 2; ++i) { const float wk = wc[16 * (ntb + i) + r16];
; #pragma unroll
;                 for (int e = 0; e < 4; ++e) { Sacc[i][e] *= wk; S2acc[i][e] *= wk; } }
;             __syncthreads();
;             if (!PA) { const size_t orow = cbase + (d ? 63 - j : j); *(u32x4_t*)(Op + orow * 1024 + hc8) = *(const u32x4_t*)(MAT(7) + j * 72 + c8); }
	v_mfma_f32_16x16x32_bf16 v[14:17], v[26:29], v[30:33], v[14:17]
	v_mfma_f32_16x16x32_bf16 v[22:25], v[26:29], v[36:39], v[22:25]
	ds_read_b128 v[26:29], v107
	ds_read_b128 v[30:33], v89 offset:55296
	s_waitcnt lgkmcnt(0)
	v_mfma_f32_16x16x32_bf16 v[18:21], v[26:29], v[30:33], v[18:21]
	ds_read_b128 v[30:33], v89 offset:57600
	s_waitcnt lgkmcnt(0)
	v_mfma_f32_16x16x32_bf16 v[10:13], v[26:29], v[30:33], v[10:13]
	ds_read_b128 v[26:29], v107 offset:64
	ds_read_b128 v[30:33], v89 offset:55360
	s_waitcnt lgkmcnt(0)
	v_mfma_f32_16x16x32_bf16 v[18:21], v[26:29], v[30:33], v[18:21]
	ds_read_b128 v[30:33], v89 offset:57664
	s_waitcnt lgkmcnt(0)
	v_mfma_f32_16x16x32_bf16 v[10:13], v[26:29], v[30:33], v[10:13]
	s_nop 4
	v_cvt_pk_bf16_f32 v18, v18, v19
	v_cvt_pk_bf16_f32 v19, v20, v21
	ds_write_b64 v108, v[18:19] offset:64512
	v_cvt_pk_bf16_f32 v10, v10, v11
	v_cvt_pk_bf16_f32 v11, v12, v13
	ds_write_b64 v109, v[10:11]
	s_waitcnt lgkmcnt(0)
	s_barrier
	ds_read_b128 v[10:13], v110
	ds_read_b128 v[18:21], v89 offset:64512
	ds_read_b128 v[26:29], v105
	s_waitcnt lgkmcnt(1)
	v_mfma_f32_16x16x32_bf16 v[18:21], v[10:13], v[18:21], 0
	s_waitcnt lgkmcnt(0)
	v_mfma_f32_16x16x32_bf16 v[10:13], v[10:13], v[26:29], 0
	ds_read_b128 v[26:29], v110 offset:64
	ds_read_b128 v[30:33], v89 offset:64576
	s_waitcnt lgkmcnt(0)
	v_mfma_f32_16x16x32_bf16 v[18:21], v[26:29], v[30:33], v[18:21]
	ds_read_b128 v[30:33], v106
	s_waitcnt lgkmcnt(0)
	v_mfma_f32_16x16x32_bf16 v[10:13], v[26:29], v[30:33], v[10:13]
	s_nop 4
	v_cvt_pk_bf16_f32 v18, v18, v19
	v_cvt_pk_bf16_f32 v19, v20, v21
	ds_write_b64 v111, v[18:19]
	v_cvt_pk_bf16_f32 v10, v10, v11
	v_cvt_pk_bf16_f32 v11, v12, v13
	ds_write_b64 v111, v[10:11] offset:2304
	s_waitcnt lgkmcnt(0)
	s_barrier
	ds_read_b128 v[10:13], v112
	ds_read_b128 v[18:21], v113
	s_waitcnt lgkmcnt(0)
	v_mfma_f32_16x16x32_bf16 v[14:17], v[10:13], v[18:21], v[14:17]
	ds_read_b128 v[18:21], v113 offset:2304
	s_waitcnt lgkmcnt(0)
	v_mfma_f32_16x16x32_bf16 v[10:13], v[10:13], v[18:21], v[22:25]
	ds_read_b128 v[18:21], v112 offset:64
	s_nop 1
	ds_read_b128 v[22:25], v113 offset:64
	s_waitcnt lgkmcnt(0)
	v_mfma_f32_16x16x32_bf16 v[14:17], v[18:21], v[22:25], v[14:17]
	ds_read_b128 v[22:25], v113 offset:2368
	s_waitcnt lgkmcnt(0)
	v_mfma_f32_16x16x32_bf16 v[10:13], v[18:21], v[22:25], v[10:13]
	ds_read_b128 v[18:21], v114
	ds_read_b128 v[22:25], v89 offset:55296
	s_waitcnt lgkmcnt(0)
	v_mfma_f32_16x16x32_bf16 v[14:17], v[18:21], v[22:25], v[14:17]
	ds_read_b128 v[22:25], v89 offset:57600
	s_waitcnt lgkmcnt(0)
	v_mfma_f32_16x16x32_bf16 v[10:13], v[18:21], v[22:25], v[10:13]
	ds_read_b128 v[18:21], v114 offset:64
	ds_read_b128 v[22:25], v89 offset:55360
	s_waitcnt lgkmcnt(0)
	v_mfma_f32_16x16x32_bf16 v[14:17], v[18:21], v[22:25], v[14:17]
	ds_read_b128 v[22:25], v89 offset:57664
	s_waitcnt lgkmcnt(0)
	v_mfma_f32_16x16x32_bf16 v[10:13], v[18:21], v[22:25], v[10:13]
	s_nop 4
	v_cvt_pk_bf16_f32 v0, v14, v15
	v_cvt_pk_bf16_f32 v14, v16, v17
	ds_write_b16 v87, v0 offset:64512
	ds_write_b16_d16_hi v87, v0 offset:64656
	ds_write_b16 v87, v14 offset:64800
	ds_write_b16_d16_hi v87, v14 offset:64944
	v_cvt_pk_bf16_f32 v0, v10, v11
	v_cvt_pk_bf16_f32 v10, v12, v13
	ds_write_b16 v87, v0 offset:64544
	ds_write_b16_d16_hi v87, v0 offset:64688
	ds_write_b16 v87, v10 offset:64832
	ds_write_b16_d16_hi v87, v10 offset:64976
	ds_read_b128 v[10:13], v115
	ds_read_b128 v[14:17], v89 offset:36864
	s_waitcnt lgkmcnt(0)
	v_mfma_f32_16x16x32_bf16 v[6:9], v[10:13], v[14:17], v[6:9]
	ds_read_b128 v[14:17], v89 offset:39168
	s_waitcnt lgkmcnt(0)
	v_mfma_f32_16x16x32_bf16 v[2:5], v[10:13], v[14:17], v[2:5]
	ds_read_b128 v[10:13], v115 offset:64
	ds_read_b128 v[14:17], v89 offset:36928
	s_waitcnt lgkmcnt(0)
	v_mfma_f32_16x16x32_bf16 v[6:9], v[10:13], v[14:17], v[6:9]
	ds_read_b128 v[14:17], v89 offset:39232
	s_waitcnt lgkmcnt(0)
	v_mfma_f32_16x16x32_bf16 v[2:5], v[10:13], v[14:17], v[2:5]
	ds_read_b128 v[10:13], v92 offset:55296
	ds_read_b128 v[14:17], v89 offset:46080
	s_waitcnt lgkmcnt(0)
	v_mfma_f32_16x16x32_bf16 v[6:9], v[10:13], v[14:17], v[6:9]
	ds_read_b128 v[14:17], v89 offset:48384
	s_waitcnt lgkmcnt(0)
	v_mfma_f32_16x16x32_bf16 v[2:5], v[10:13], v[14:17], v[2:5]
	ds_read_b128 v[10:13], v92 offset:55360
	ds_read_b128 v[14:17], v89 offset:46144
	ds_read_b32 v0, v127
	s_waitcnt lgkmcnt(1)
	v_mfma_f32_16x16x32_bf16 v[6:9], v[10:13], v[14:17], v[6:9]
	ds_read_b128 v[14:17], v89 offset:48448
	s_waitcnt lgkmcnt(0)
	v_mfma_f32_16x16x32_bf16 v[2:5], v[10:13], v[14:17], v[2:5]
	s_nop 4
	v_mul_f32_e64 v6, v6, v0
	v_mul_f32_e64 v7, v7, v0
	v_pk_mul_f32 v[8:9], v[8:9], v[0:1] op_sel_hi:[1,0]
	ds_read_b32 v0, v128
	s_waitcnt lgkmcnt(0)
	s_barrier
	ds_read_b128 v[10:13], v91 offset:64512
	v_pk_mul_f32 v[2:3], v[2:3], v[0:1] op_sel_hi:[1,0]
	v_pk_mul_f32 v[4:5], v[4:5], v[0:1] op_sel_hi:[1,0]
	v_lshl_add_u64 v[14:15], v[34:35], 1, v[76:77]
	s_waitcnt lgkmcnt(0)
	global_store_dwordx4 v[14:15], v[10:13], off
	s_cbranch_scc1 .LBB0_128
; template <bool PA> ...
;     ...
;             const int cidx = d ? nch - 1 - p : p; const int cbase = seqbase + cidx * 64;
;             float rv[8], kk[8], av[8], kd[8], lw[8]; u32x4_t tld = (u32x4_t){0u, 0u, 0u, 0u}, vraw = (u32x4_t){0u, 0u, 0u, 0u};
;             {
;                 const size_t row = cbase + (d ? 63 - j : j);
;                 asm volatile("" ::: "memory");
;                 if (haveT && tlow) tld = *(const u32x4_t*)(tbuf + ((size_t)strm * NCHA + p) * 2304 + tunit * 8);
;                 *(u32x4_t*)(MAT(4) + j * 72 + c8) = *(const u32x4_t*)(HWb + row * 128 + d * 64 + c8);
;                 *(u32x4_t*)(MAT(5) + j * 72 + c8) = *(const u32x4_t*)(HAb + row * 128 + d * 64 + c8);
;                 const u32x4_t rw = *(const u32x4_t*)(Rb + row * 1024 + hc8), kw = *(const u32x4_t*)(Kb + row * 1024 + hc8), vw = *(const u32x4_t*)(Vb + row * 1024 + hc8);
;                 __syncthreads();
;                 { f32x4_t za[2], xa[2]; za[0] = (f32x4_t){0.f, 0.f, 0.f, 0.f}; za[1] = za[0]; xa[0] = za[0]; xa[1] = za[0];
;                   mm2(za, MAT(4), w2T, mt, ntb, r16, kq); mm2(xa, MAT(5), a2T, mt, ntb, r16, kq);
; #pragma unroll
;                   for (int i = 0; i < 2; ++i)
; #pragma unroll
;                       for (int e = 0; e < 4; ++e) { zbuf[(16 * mt + 4 * kq + e) * 64 + 16 * (ntb + i) + r16] = za[i][e]; abuf[(16 * mt + 4 * kq + e) * 64 + 16 * (ntb + i) + r16] = xa[i][e]; } }
;                 __syncthreads();
.LBB0_153:
	s_nop 0
	s_waitcnt vmcnt(2)
	ds_write_b128 v91, v[232:235] offset:36864
	ds_write_b128 v91, v[236:239] offset:46080
	v_mov_b32_e32 v10, v228
	v_mov_b32_e32 v11, v229
	v_mov_b32_e32 v12, v230
	v_mov_b32_e32 v13, v231
	v_mov_b32_e32 v18, v240
	v_mov_b32_e32 v19, v241
	v_mov_b32_e32 v20, v242
	v_mov_b32_e32 v21, v243
	v_mov_b32_e32 v22, v244
	v_mov_b32_e32 v23, v245
	v_mov_b32_e32 v24, v246
	v_mov_b32_e32 v25, v247
	v_mov_b32_e32 v14, v248
	v_mov_b32_e32 v15, v249
	v_mov_b32_e32 v16, v250
	v_mov_b32_e32 v17, v251
	s_and_b64 s[0:1], vcc, exec
	s_cselect_b32 s0, s12, s18
	v_lshl_add_u32 v80, s0, 6, v130
	v_ashrrev_i32_e32 v81, 31, v80
	s_add_i32 s1, s12, 1
	s_cmp_lt_i32 s1, s13
	s_cselect_b32 s1, 1, 0
	s_add_i32 s0, s12, s1
	s_sub_i32 s1, s18, s1
	s_and_b64 s[98:99], vcc, exec
	s_cselect_b32 s0, s0, s1
	v_lshl_add_u32 v226, s0, 6, v130
	s_and_saveexec_b64 s[0:1], s[36:37]
	global_load_dwordx4 v[228:231], v[78:79], off
	s_or_b64 exec, exec, s[0:1]
	v_ashrrev_i32_e32 v227, 31, v226
	v_lshlrev_b64 v[224:225], 8, v[226:227]
	v_lshl_add_u64 v[222:223], v[66:67], 0, v[224:225]
	global_load_dwordx4 v[232:235], v[222:223], off
	v_lshl_add_u64 v[222:223], v[68:69], 0, v[224:225]
	global_load_dwordx4 v[236:239], v[222:223], off
	v_lshlrev_b64 v[224:225], 11, v[226:227]
	v_lshl_add_u64 v[222:223], v[70:71], 0, v[224:225]
	global_load_dwordx4 v[240:243], v[222:223], off
	v_lshl_add_u64 v[222:223], v[72:73], 0, v[224:225]
	global_load_dwordx4 v[244:247], v[222:223], off
	v_lshl_add_u64 v[222:223], v[74:75], 0, v[224:225]
	global_load_dwordx4 v[248:251], v[222:223], off
	s_waitcnt lgkmcnt(0)
	s_barrier
	ds_read_b128 v[26:29], v92 offset:36864
	ds_read_b128 v[30:33], v93
	ds_read_b128 v[34:37], v93 offset:2304
	s_waitcnt lgkmcnt(1)
	v_mfma_f32_16x16x32_bf16 v[30:33], v[26:29], v[30:33], 0
	s_nop 0
	v_lshlrev_b32_e32 v0, 16, v18
	s_waitcnt lgkmcnt(0)
	v_mfma_f32_16x16x32_bf16 v[26:29], v[26:29], v[34:37], 0
	ds_read_b128 v[34:37], v92 offset:36928
	ds_read_b128 v[38:41], v93 offset:64
	v_and_b32_e32 v131, 0xffff0000, v18
	s_nop 0
	v_and_b32_e32 v162, 0xffff0000, v24
	s_waitcnt lgkmcnt(0)
	v_mfma_f32_16x16x32_bf16 v[30:33], v[34:37], v[38:41], v[30:33]
	ds_read_b128 v[38:41], v93 offset:2368
	v_lshlrev_b32_e32 v141, 16, v21
	v_and_b32_e32 v143, 0xffff0000, v21
	s_waitcnt lgkmcnt(0)
	v_mfma_f32_16x16x32_bf16 v[26:29], v[34:37], v[38:41], v[26:29]
	ds_read_b128 v[34:37], v92 offset:46080
	ds_read_b128 v[38:41], v94
	ds_read_b128 v[132:135], v94 offset:2304
	v_lshlrev_b32_e32 v158, 16, v25
	s_waitcnt lgkmcnt(1)
	v_mfma_f32_16x16x32_bf16 v[38:41], v[34:37], v[38:41], 0
	v_and_b32_e32 v154, 0xffff0000, v25
	s_waitcnt lgkmcnt(0)
	v_mfma_f32_16x16x32_bf16 v[34:37], v[34:37], v[132:135], 0
	ds_read_b128 v[132:135], v92 offset:46144
	ds_read_b128 v[136:139], v94 offset:64
	s_waitcnt lgkmcnt(0)
	v_mfma_f32_16x16x32_bf16 v[38:41], v[132:135], v[136:139], v[38:41]
	ds_read_b128 v[136:139], v94 offset:2368
	s_waitcnt lgkmcnt(0)
	v_mfma_f32_16x16x32_bf16 v[34:37], v[132:135], v[136:139], v[34:37]
	s_nop 4
	ds_write2st64_b32 v119, v30, v38 offset1:64
	ds_write2st64_b32 v120, v31, v39 offset1:64
	ds_write2st64_b32 v121, v32, v40 offset1:64
	ds_write2st64_b32 v122, v33, v41 offset1:64
	ds_write2st64_b32 v123, v26, v34 offset1:64
	ds_write2st64_b32 v124, v27, v35 offset1:64
	ds_write2st64_b32 v125, v28, v36 offset1:64
	ds_write2st64_b32 v126, v29, v37 offset1:64
	s_waitcnt lgkmcnt(0)
	s_barrier
; __device__ __forceinline__ float sigmoidf_(float x) { return __builtin_amdgcn_rcpf(1.0f + __expf(-x)); }
; template <bool PA> ...
;     ...
;                 const unsigned rwa[4] = {rw.x, rw.y, rw.z, rw.w}, kwa[4] = {kw.x, kw.y, kw.z, kw.w};
;                 float kv[8], z[8], aa[8];
; #pragma unroll
;                 for (int q = 0; q < 4; ++q) { rv[2 * q] = __uint_as_float(rwa[q] << 16); rv[2 * q + 1] = __uint_as_float(rwa[q] & 0xffff0000u); kv[2 * q] = __uint_as_float(kwa[q] << 16); kv[2 * q + 1] = __uint_as_float(kwa[q] & 0xffff0000u);
;                 }
;                 vraw = vw;
;                 { const f32x4_t z0 = *(const f32x4_t*)(zbuf + j * 64 + c8), z1 = *(const f32x4_t*)(zbuf + j * 64 + c8 + 4), x0 = *(const f32x4_t*)(abuf + j * 64 + c8), x1 = *(const f32x4_t*)(abuf + j * 64 + c8 + 4);
; #pragma unroll
;                   for (int e = 0; e < 4; ++e) { z[e] = cst[c8 + e] + z0[e]; z[4 + e] = cst[c8 + 4 + e] + z1[e]; aa[e] = cst[64 + c8 + e] + x0[e]; aa[4 + e] = cst[64 + c8 + 4 + e] + x1[e]; } }
;                 asm volatile("" ::: "memory");
;                 float ss = 0.f, bsum = 0.f;
; #pragma unroll
;                 for (int e = 0; e < 8; ++e) { kk[e] = kv[e] * cst[128 + c8 + e]; ss += kk[e] * kk[e]; }
;                 ss += __shfl_xor(ss, 1); ss += __shfl_xor(ss, 2); ss += __shfl_xor(ss, 4);
;                 const float inv = rsqrtf(fmaxf(ss, 1e-24f));
; #pragma unroll
;                 for (int e = 0; e < 8; ++e) { av[e] = sigmoidf_(aa[e]); lw[e] = -0.6065306597f * sigmoidf_(z[e]); kd[e] = kv[e] * (1.0f + (av[e] - 1.0f) * cst[192 + c8 + e]); kk[e] *= inv; bsum += rv[e] * kd[e] * cst[256 + c8 + e]; }
;                 bsum += __shfl_xor(bsum, 1); bsum += __shfl_xor(bsum, 2); bsum += __shfl_xor(bsum, 4);
;                 if (!PA && part == 0) beta[((size_t)d * SLAB + row) * 16 + head] = bsum;
	v_lshlrev_b32_e32 v39, 16, v22
	v_and_b32_e32 v36, 0xffff0000, v22
	v_lshlrev_b32_e32 v133, 16, v19
	v_and_b32_e32 v135, 0xffff0000, v19
	v_lshlrev_b32_e32 v35, 16, v23
	v_and_b32_e32 v34, 0xffff0000, v23
	v_lshlrev_b32_e32 v137, 16, v20
	v_and_b32_e32 v139, 0xffff0000, v20
	v_lshlrev_b32_e32 v38, 16, v24
	ds_read_b128 v[18:21], v95
	ds_read_b128 v[22:25], v95 offset:16
	ds_read_b128 v[144:147], v95 offset:16384
	ds_read_b128 v[148:151], v95 offset:16400
	ds_read_b128 v[26:29], v96
	ds_read_b128 v[30:33], v96 offset:16
	ds_read_b128 v[164:167], v96 offset:256
	ds_read_b128 v[168:171], v96 offset:272
	s_waitcnt lgkmcnt(1)
	v_add_f32_e32 v153, v144, v164
	s_waitcnt lgkmcnt(0)
	v_add_f32_e32 v37, v148, v168
	v_add_f32_e32 v152, v145, v165
	v_add_f32_e32 v164, v149, v169
	v_add_f32_e32 v41, v146, v166
	v_add_f32_e32 v161, v150, v170
	v_add_f32_e32 v40, v147, v167
	v_add_f32_e32 v157, v151, v171
	ds_read_b128 v[144:147], v96 offset:512
	ds_read_b128 v[148:151], v96 offset:528
	ds_read_b128 v[168:171], v96 offset:768
	ds_read_b128 v[172:175], v96 offset:1024
	s_waitcnt lgkmcnt(3)
	v_mul_f32_e32 v134, v145, v36
	v_mul_f32_e32 v132, v144, v39
	v_mul_f32_e32 v155, v134, v134
	v_fmac_f32_e32 v155, v132, v132
	v_mul_f32_e32 v136, v146, v35
	v_fmac_f32_e32 v155, v136, v136
	v_mul_f32_e32 v138, v147, v34
	v_fmac_f32_e32 v155, v138, v138
	s_waitcnt lgkmcnt(2)
	v_mul_f32_e32 v140, v148, v38
	v_and_b32_e32 v147, 64, v198
	v_fmac_f32_e32 v155, v140, v140
	v_mul_f32_e32 v142, v149, v162
	v_xor_b32_e32 v146, 1, v198
	v_add_u32_e32 v147, 64, v147
	v_fmac_f32_e32 v155, v142, v142
	v_mul_f32_e32 v144, v150, v158
	v_cmp_lt_i32_e64 s[92:93], v146, v147
	v_fmac_f32_e32 v155, v144, v144
	v_mul_f32_e32 v145, v151, v154
	v_cndmask_b32_e64 v146, v198, v146, s[92:93]
	v_fmac_f32_e32 v155, v145, v145
	v_lshlrev_b32_e32 v146, 2, v146
	ds_bpermute_b32 v148, v146, v155
	v_xor_b32_e32 v149, 2, v198
	v_cmp_lt_i32_e64 s[92:93], v149, v147
	s_waitcnt lgkmcnt(0)
	v_add_f32_e32 v148, v155, v148
	v_cndmask_b32_e64 v149, v198, v149, s[92:93]
	v_lshlrev_b32_e32 v166, 2, v149
	ds_bpermute_b32 v149, v166, v148
	s_waitcnt lgkmcnt(0)
	v_add_f32_e32 v149, v148, v149
	v_xor_b32_e32 v148, 4, v198
	v_cmp_lt_i32_e64 s[92:93], v148, v147
	s_nop 1
	v_cndmask_b32_e64 v147, v198, v148, s[92:93]
	v_mul_f32_e32 v148, 0xbfb8aa3b, v153
	v_exp_f32_e32 v148, v148
	v_lshlrev_b32_e32 v147, 2, v147
	ds_bpermute_b32 v150, v147, v149
	v_add_f32_e32 v148, 1.0, v148
	v_rcp_f32_e32 v148, v148
	s_nop 0
	v_add_f32_e32 v151, -1.0, v148
	v_fma_f32 v151, v151, v168, 1.0
	v_mul_f32_e32 v151, v151, v39
	v_mul_f32_e32 v39, v151, v0
	v_fma_f32 v167, v172, v39, 0
	v_mul_f32_e32 v39, 0xbfb8aa3b, v152
	v_exp_f32_e32 v39, v39
	s_nop 0
	v_add_f32_e32 v39, 1.0, v39
	v_rcp_f32_e32 v152, v39
	s_nop 0
	v_add_f32_e32 v39, -1.0, v152
	v_fma_f32 v39, v39, v169, 1.0
	v_mul_f32_e32 v153, v39, v36
	v_mul_f32_e32 v36, v153, v131
	v_fmac_f32_e32 v167, v173, v36
	v_mul_f32_e32 v36, 0xbfb8aa3b, v41
	v_exp_f32_e32 v36, v36
	s_nop 0
	v_add_f32_e32 v36, 1.0, v36
	v_rcp_f32_e32 v155, v36
	s_nop 0
	v_add_f32_e32 v36, -1.0, v155
	v_fma_f32 v36, v36, v170, 1.0
	v_mul_f32_e32 v156, v36, v35
	v_mul_f32_e32 v35, v156, v133
	v_fmac_f32_e32 v167, v174, v35
	v_mul_f32_e32 v35, 0xbfb8aa3b, v40
	v_exp_f32_e32 v35, v35
	s_nop 0
	v_add_f32_e32 v35, 1.0, v35
	v_rcp_f32_e32 v159, v35
	s_nop 0
	v_add_f32_e32 v35, -1.0, v159
	v_fma_f32 v35, v35, v171, 1.0
	v_mul_f32_e32 v160, v35, v34
	v_mul_f32_e32 v34, v160, v135
	v_fmac_f32_e32 v167, v175, v34
	v_mul_f32_e32 v34, 0xbfb8aa3b, v37
	v_exp_f32_e32 v34, v34
	s_nop 0
	v_add_f32_e32 v34, 1.0, v34
	v_rcp_f32_e32 v163, v34
	ds_read_b128 v[34:37], v96 offset:784
	v_add_f32_e32 v39, -1.0, v163
	s_waitcnt lgkmcnt(0)
	v_fma_f32 v34, v39, v34, 1.0
	v_mul_f32_e32 v165, v34, v38
	ds_read_b128 v[38:41], v96 offset:1040
	v_mul_f32_e32 v34, v165, v137
	s_waitcnt lgkmcnt(0)
	v_fmac_f32_e32 v167, v38, v34
	v_mul_f32_e32 v34, 0xbfb8aa3b, v164
	v_exp_f32_e32 v34, v34
	s_nop 0
	v_add_f32_e32 v34, 1.0, v34
	v_rcp_f32_e32 v38, v34
	s_nop 0
	v_add_f32_e32 v34, -1.0, v38
	v_fma_f32 v34, v34, v35, 1.0
	v_mul_f32_e32 v162, v34, v162
	v_mul_f32_e32 v34, v162, v139
	v_fmac_f32_e32 v167, v39, v34
	v_mul_f32_e32 v34, 0xbfb8aa3b, v161
	v_exp_f32_e32 v34, v34
	s_nop 0
	v_add_f32_e32 v34, 1.0, v34
	v_rcp_f32_e32 v39, v34
	s_nop 0
	v_add_f32_e32 v34, -1.0, v39
	v_fma_f32 v34, v34, v36, 1.0
	v_mul_f32_e32 v36, v34, v158
	v_mul_f32_e32 v34, v36, v141
	v_fmac_f32_e32 v167, v40, v34
	v_mul_f32_e32 v34, 0xbfb8aa3b, v157
	v_exp_f32_e32 v34, v34
	s_nop 0
	v_add_f32_e32 v34, 1.0, v34
	v_rcp_f32_e32 v40, v34
	s_nop 0
	v_add_f32_e32 v34, -1.0, v40
	v_fma_f32 v34, v34, v37, 1.0
	v_mul_f32_e32 v37, v34, v154
	v_mul_f32_e32 v34, v37, v143
	v_fmac_f32_e32 v167, v41, v34
	ds_bpermute_b32 v34, v146, v167
	s_waitcnt lgkmcnt(0)
	v_add_f32_e32 v34, v167, v34
	ds_bpermute_b32 v35, v166, v34
	s_waitcnt lgkmcnt(0)
	v_add_f32_e32 v34, v34, v35
	ds_bpermute_b32 v35, v147, v34
	s_and_saveexec_b64 s[0:1], s[44:45]
	s_cbranch_execz .LBB0_157
	v_lshl_add_u64 v[146:147], s[24:25], 0, v[80:81]
	v_lshlrev_b64 v[146:147], 6, v[146:147]
	v_lshl_add_u64 v[146:147], s[20:21], 0, v[146:147]
	s_waitcnt lgkmcnt(0)
	v_add_f32_e32 v34, v34, v35
	global_store_dword v[146:147], v34, off

; template <bool PA> ...
;     ...
;         const int g = item % G, strm = item / G; const int p0 = g == 0 ? 0 : 1 + 32 * g, p1 = 33 + 32 * g;
;         const bool haveT = !PA;
;         const int d = strm & 1, head = (strm >> 1) & 15, sq = strm >> 5; const int seqbase = sq * 8256; const int hc8 = head * 64 + c8;
;         bf16* Op = d ? OBb : OFb;
;         const float* w0 = a->in[15] + d * 1024; const float* w2 = a->in[17] + (size_t)d * 64 * 1024; const float* a0 = a->in[18] + d * 1024; const float* a2 = a->in[20] + (size_t)d * 64 * 1024;
;         __syncthreads();
;         if (tid < 320) { const int wch = tid >> 6, cc = tid & 63; const float* src = wch == 0 ? w0 : (wch == 1 ? a0 : (wch == 2 ? a->in[23] : (wch == 3 ? a->in[24] : a->in[25]))); cst[tid] = src[head * 64 + cc]; }
;         for (int i = tid; i < 4096; i += 512) { const int l = i >> 6, cc = i & 63; w2T[cc * 72 + l] = (bf16)f2bf(w2[(size_t)l * 1024 + head * 64 + cc]); a2T[cc * 72 + l] = (bf16)f2bf(a2[(size_t)l * 1024 + head * 64 + cc]); }
;         f32x4_t Sacc[2], S2acc[2]; Sacc[0] = (f32x4_t){0.f, 0.f, 0.f, 0.f}; Sacc[1] = Sacc[0];
; #pragma unroll
;         for (int i = 0; i < 2; ++i)
; #pragma unroll
;             for (int e = 0; e < 4; ++e) S2acc[i][e] = (16 * mt + 4 * kq + e == 16 * (ntb + i) + r16) ? 1.f : 0.f;
;         __syncthreads();
;         if (!PA) {
;             for (int gg = 0; gg < g; ++gg) {
;                 const float* Psi = segm + (size_t)(strm * G + gg) * 8192; const float* Phi = Psi + 4096;
;                 { const f32x4_t q0 = *(const f32x4_t*)(Phi + j * 64 + c8), q1 = *(const f32x4_t*)(Phi + j * 64 + c8 + 4);
; #pragma unroll
;                   for (int e = 0; e < 4; ++e) { MAT(1)[(c8 + e) * 72 + j] = (bf16)f2bf(q0[e]); MAT(1)[(c8 + 4 + e) * 72 + j] = (bf16)f2bf(q1[e]); } }
;                 st_rm(MAT(0), Sacc, mt, ntb, r16, kq);
;                 __syncthreads();
; #pragma unroll
;                 for (int i = 0; i < 2; ++i)
; #pragma unroll
;                     for (int e = 0; e < 4; ++e) Sacc[i][e] = Psi[(16 * mt + 4 * kq + e) * 64 + 16 * (ntb + i) + r16];
;                 mm2(Sacc, MAT(0), MAT(1), mt, ntb, r16, kq);
;                 __syncthreads();
;             }
;         }
;         for (int p = p0; p < p1; ++p) {
;             const int cidx = d ? nch - 1 - p : p; const int cbase = seqbase + cidx * 64;
.LBB0_211:
	s_or_b64 exec, exec, s[12:13]
	s_mul_i32 s12, s15, s78
	s_sub_i32 s12, s82, s12
	s_lshl_b32 s21, s12, 5
	s_or_b32 s13, s21, 1
	s_cmp_lg_u32 s12, 0
	s_cselect_b32 s20, s13, 0
	s_add_i32 s21, s21, 33
	v_mov_b32_e32 v9, 0
	s_cmp_lt_i32 s20, s21
	v_mov_b32_e32 v8, v9
	v_mov_b32_e32 v7, v9
	v_mov_b32_e32 v6, v9
	v_mov_b32_e32 v5, v9
	v_mov_b32_e32 v4, v9
	v_mov_b32_e32 v3, v9
	v_mov_b32_e32 v2, v9
	v_mov_b32_e32 v17, v143
	v_mov_b32_e32 v16, v142
	v_mov_b32_e32 v15, v141
	v_mov_b32_e32 v14, v140
	v_mov_b32_e32 v13, v139
	v_mov_b32_e32 v12, v138
	v_mov_b32_e32 v11, v137
	v_mov_b32_e32 v10, v136
	s_waitcnt lgkmcnt(0)
	s_barrier
	s_cbranch_scc0 .LBB0_193
	s_lshr_b32 s12, s15, 5
	s_cmp_eq_u32 s24, 0
	s_cselect_b64 s[74:75], -1, 0
	s_mulk_i32 s12, 0x2040
	v_cndmask_b32_e64 v2, v107, v104, s[74:75]
	s_waitcnt vmcnt(44)
	v_add_u32_e32 v160, s12, v2
	s_lshl_b32 s24, s24, 7
	s_mul_hi_i32 s12, s15, s91
	s_mul_i32 s15, s15, s91
	s_ashr_i32 s13, s20, 31
	s_add_u32 s15, s15, s20
	v_or_b32_e32 v0, s80, v105
	s_addc_u32 s12, s12, s13
	v_lshl_add_u64 v[90:91], v[66:67], 0, s[24:25]
	v_lshl_add_u64 v[92:93], v[70:71], 0, s[24:25]
	v_lshlrev_b32_e32 v0, 1, v0
	s_mul_i32 s24, s12, 0x1200
	v_mad_u64_u32 v[100:101], s[12:13], s15, v199, v[72:73]
	v_mov_b32_e32 v8, 0
	v_lshl_add_u64 v[94:95], s[0:1], 0, v[0:1]
	v_lshl_add_u64 v[96:97], s[18:19], 0, v[0:1]
	v_lshl_add_u64 v[98:99], s[22:23], 0, v[0:1]
	v_add_u32_e32 v101, s24, v101
	s_sub_i32 s24, s79, s20
	v_mov_b32_e32 v10, v136
	v_mov_b32_e32 v11, v137
	v_mov_b32_e32 v12, v138
	v_mov_b32_e32 v13, v139
	v_mov_b32_e32 v14, v140
	v_mov_b32_e32 v15, v141
	v_mov_b32_e32 v16, v142
	v_mov_b32_e32 v17, v143
	v_mov_b32_e32 v0, 0
	v_mov_b32_e32 v2, 0
	v_mov_b32_e32 v3, v8
	v_mov_b32_e32 v4, v8
	v_mov_b32_e32 v5, v8
	v_mov_b32_e32 v6, 0
	v_mov_b32_e32 v7, v8
	v_mov_b32_e32 v9, v8
	s_and_b64 s[12:13], s[74:75], exec
	s_cselect_b32 s12, s20, s24
	v_lshl_add_u32 v226, s12, 6, v160
	v_ashrrev_i32_e32 v227, 31, v226
	v_lshlrev_b64 v[224:225], 8, v[226:227]
	v_lshl_add_u64 v[222:223], v[90:91], 0, v[224:225]
	global_load_dwordx4 v[232:235], v[222:223], off
	v_lshl_add_u64 v[222:223], v[92:93], 0, v[224:225]
	global_load_dwordx4 v[236:239], v[222:223], off
	v_lshlrev_b64 v[224:225], 11, v[226:227]
	v_lshl_add_u64 v[222:223], v[94:95], 0, v[224:225]
	global_load_dwordx4 v[240:243], v[222:223], off
	v_lshl_add_u64 v[222:223], v[96:97], 0, v[224:225]
	global_load_dwordx4 v[244:247], v[222:223], off
	v_lshl_add_u64 v[222:223], v[98:99], 0, v[224:225]
	global_load_dwordx4 v[248:251], v[222:223], off
	s_waitcnt vmcnt(0)
.LBB0_213:
	s_waitcnt vmcnt(1)
	ds_write_b128 v68, v[232:235] offset:36864
	ds_write_b128 v68, v[236:239] offset:46080
	v_mov_b32_e32 v22, v240
	v_mov_b32_e32 v23, v241
	v_mov_b32_e32 v24, v242
	v_mov_b32_e32 v25, v243
	v_mov_b32_e32 v26, v244
	v_mov_b32_e32 v27, v245
	v_mov_b32_e32 v28, v246
	v_mov_b32_e32 v29, v247
	v_mov_b32_e32 v18, v248
	v_mov_b32_e32 v19, v249
	v_mov_b32_e32 v20, v250
	v_mov_b32_e32 v21, v251
	s_add_i32 s12, s20, 1
	s_cmp_lt_i32 s12, s21
	s_cselect_b32 s13, 1, 0
	s_add_i32 s12, s20, s13
	s_sub_i32 s13, s24, s13
	s_and_b64 s[98:99], s[74:75], exec
	s_cselect_b32 s12, s12, s13
	v_lshl_add_u32 v226, s12, 6, v160
	v_ashrrev_i32_e32 v227, 31, v226
	v_lshlrev_b64 v[224:225], 8, v[226:227]
	v_lshl_add_u64 v[222:223], v[90:91], 0, v[224:225]
	global_load_dwordx4 v[232:235], v[222:223], off
	v_lshl_add_u64 v[222:223], v[92:93], 0, v[224:225]
	global_load_dwordx4 v[236:239], v[222:223], off
	v_lshlrev_b64 v[224:225], 11, v[226:227]
	v_lshl_add_u64 v[222:223], v[94:95], 0, v[224:225]
	global_load_dwordx4 v[240:243], v[222:223], off
	v_lshl_add_u64 v[222:223], v[96:97], 0, v[224:225]
	global_load_dwordx4 v[244:247], v[222:223], off
	v_lshl_add_u64 v[222:223], v[98:99], 0, v[224:225]
	global_load_dwordx4 v[248:251], v[222:223], off
	s_waitcnt lgkmcnt(0)
	s_barrier
	ds_read_b128 v[30:33], v69 offset:36864
	ds_read_b128 v[34:37], v108
	ds_read_b128 v[38:41], v108 offset:2304
	s_waitcnt lgkmcnt(1)
	v_mfma_f32_16x16x32_bf16 v[34:37], v[30:33], v[34:37], 0
	s_nop 0
	v_lshlrev_b32_e32 v161, 16, v26
	s_waitcnt lgkmcnt(0)
	v_mfma_f32_16x16x32_bf16 v[30:33], v[30:33], v[38:41], 0
	ds_read_b128 v[38:41], v69 offset:36928
	ds_read_b128 v[42:45], v108 offset:64
	v_and_b32_e32 v163, 0xffff0000, v26
	v_lshlrev_b32_e32 v165, 16, v27
	s_waitcnt lgkmcnt(0)
	v_mfma_f32_16x16x32_bf16 v[34:37], v[38:41], v[42:45], v[34:37]
	ds_read_b128 v[42:45], v108 offset:2368
	v_and_b32_e32 v167, 0xffff0000, v27
	v_lshlrev_b32_e32 v169, 16, v28
	s_waitcnt lgkmcnt(0)
	v_mfma_f32_16x16x32_bf16 v[30:33], v[38:41], v[42:45], v[30:33]
	ds_read_b128 v[38:41], v69 offset:46080
	ds_read_b128 v[42:45], v109
	ds_read_b128 v[46:49], v109 offset:2304
	v_and_b32_e32 v171, 0xffff0000, v28
	s_waitcnt lgkmcnt(1)
	v_mfma_f32_16x16x32_bf16 v[42:45], v[38:41], v[42:45], 0
	v_lshlrev_b32_e32 v173, 16, v29
	v_and_b32_e32 v175, 0xffff0000, v29
	s_waitcnt lgkmcnt(0)
	v_mfma_f32_16x16x32_bf16 v[38:41], v[38:41], v[46:49], 0
	ds_read_b128 v[46:49], v69 offset:46144
	ds_read_b128 v[50:53], v109 offset:64
	s_waitcnt lgkmcnt(0)
	v_mfma_f32_16x16x32_bf16 v[42:45], v[46:49], v[50:53], v[42:45]
	ds_read_b128 v[50:53], v109 offset:2368
	s_waitcnt lgkmcnt(0)
	v_mfma_f32_16x16x32_bf16 v[38:41], v[46:49], v[50:53], v[38:41]
	s_nop 4
	ds_write2st64_b32 v144, v34, v42 offset1:64
	ds_write2st64_b32 v145, v35, v43 offset1:64
	ds_write2st64_b32 v148, v36, v44 offset1:64
	ds_write2st64_b32 v149, v37, v45 offset1:64
	ds_write2st64_b32 v150, v30, v38 offset1:64
	ds_write2st64_b32 v151, v31, v39 offset1:64
	ds_write2st64_b32 v152, v32, v40 offset1:64
	ds_write2st64_b32 v153, v33, v41 offset1:64
	s_waitcnt lgkmcnt(0)
	s_barrier
; __device__ __forceinline__ float sigmoidf_(float x) { return __builtin_amdgcn_rcpf(1.0f + __expf(-x)); }
; template <bool PA> ...
;     ...
;                 { const f32x4_t z0 = *(const f32x4_t*)(zbuf + j * 64 + c8), z1 = *(const f32x4_t*)(zbuf + j * 64 + c8 + 4), x0 = *(const f32x4_t*)(abuf + j * 64 + c8), x1 = *(const f32x4_t*)(abuf + j * 64 + c8 + 4);
; #pragma unroll
;                   for (int e = 0; e < 4; ++e) { z[e] = cst[c8 + e] + z0[e]; z[4 + e] = cst[c8 + 4 + e] + z1[e]; aa[e] = cst[64 + c8 + e] + x0[e]; aa[4 + e] = cst[64 + c8 + 4 + e] + x1[e]; } }
;                 asm volatile("" ::: "memory");
;                 float ss = 0.f, bsum = 0.f;
; #pragma unroll
;                 for (int e = 0; e < 8; ++e) { kk[e] = kv[e] * cst[128 + c8 + e]; ss += kk[e] * kk[e]; }
;                 ss += __shfl_xor(ss, 1); ss += __shfl_xor(ss, 2); ss += __shfl_xor(ss, 4);
;                 const float inv = rsqrtf(fmaxf(ss, 1e-24f));
; #pragma unroll
;                 for (int e = 0; e < 8; ++e) { av[e] = sigmoidf_(aa[e]); lw[e] = -0.6065306597f * sigmoidf_(z[e]); kd[e] = kv[e] * (1.0f + (av[e] - 1.0f) * cst[192 + c8 + e]); kk[e] *= inv; bsum += rv[e] * kd[e] * cst[256 + c8 + e]; }
;                 bsum += __shfl_xor(bsum, 1); bsum += __shfl_xor(bsum, 2); bsum += __shfl_xor(bsum, 4);
;                 if (!PA && part == 0) beta[((size_t)d * SLAB + row) * 16 + head] = bsum;
;                 *(f32x4_t*)(cumb + j * 64 + c8) = (f32x4_t){lw[0], lw[1], lw[2], lw[3]}; *(f32x4_t*)(cumb + j * 64 + c8 + 4) = (f32x4_t){lw[4], lw[5], lw[6], lw[7]};
;             }
;             __syncthreads();
;             { const int c = tid & 63, sg = tid >> 6; float run = 0.f;
; #pragma unroll
;               for (int i = 0; i < 8; ++i) { run += cumb[(8 * sg + i) * 64 + c]; cumb[(8 * sg + i) * 64 + c] = run; }
;               segtot[sg * 64 + c] = run; }
;             __syncthreads();
;             { const int c = tid & 63, sg = tid >> 6; float off = 0.f;
; #pragma unroll
;               for (int s = 0; s < 7; ++s) off += (s < sg) ? segtot[s * 64 + c] : 0.f;
; #pragma unroll
;               for (int i = 0; i < 8; ++i) cumb[(8 * sg + i) * 64 + c] += off; }
	ds_read_b128 v[42:45], v110
	ds_read_b128 v[50:53], v110 offset:16
	ds_read_b128 v[26:29], v110 offset:16384
	ds_read_b128 v[30:33], v110 offset:16400
	ds_read_b128 v[56:59], v111
	ds_read_b128 v[60:63], v111 offset:16
	ds_read_b128 v[34:37], v111 offset:256
	ds_read_b128 v[38:41], v111 offset:272
	s_waitcnt lgkmcnt(3)
	v_add_f32_e32 v42, v42, v56
	s_waitcnt lgkmcnt(2)
	v_add_f32_e32 v50, v50, v60
	v_add_f32_e32 v46, v43, v57
	v_add_f32_e32 v54, v51, v61
	v_add_f32_e32 v49, v44, v58
	v_add_f32_e32 v57, v52, v62
	v_add_f32_e32 v48, v45, v59
	v_add_f32_e32 v56, v53, v63
	ds_read_b128 v[58:61], v111 offset:512
	ds_read_b128 v[62:65], v111 offset:528
	v_and_b32_e32 v45, 64, v198
	v_xor_b32_e32 v44, 1, v198
	v_add_u32_e32 v45, 64, v45
	s_waitcnt lgkmcnt(1)
	v_mul_f32_e32 v164, v59, v163
	v_mul_f32_e32 v162, v58, v161
	v_mul_f32_e32 v43, v164, v164
	v_fmac_f32_e32 v43, v162, v162
	v_mul_f32_e32 v166, v60, v165
	v_fmac_f32_e32 v43, v166, v166
	v_mul_f32_e32 v168, v61, v167
	v_fmac_f32_e32 v43, v168, v168
	s_waitcnt lgkmcnt(0)
	v_mul_f32_e32 v170, v62, v169
	v_fmac_f32_e32 v43, v170, v170
	v_mul_f32_e32 v172, v63, v171
	v_fmac_f32_e32 v43, v172, v172
	v_mul_f32_e32 v174, v64, v173
	v_cmp_lt_i32_e64 s[76:77], v44, v45
	v_fmac_f32_e32 v43, v174, v174
	v_mul_f32_e32 v176, v65, v175
	v_cndmask_b32_e64 v44, v198, v44, s[76:77]
	v_fmac_f32_e32 v43, v176, v176
	v_lshlrev_b32_e32 v44, 2, v44
	ds_bpermute_b32 v44, v44, v43
	v_mul_f32_e32 v42, 0xbfb8aa3b, v42
	v_mul_f32_e32 v46, 0xbfb8aa3b, v46
	v_exp_f32_e32 v42, v42
	v_exp_f32_e32 v46, v46
	v_mul_f32_e32 v50, 0xbfb8aa3b, v50
	v_mul_f32_e32 v54, 0xbfb8aa3b, v54
	s_waitcnt lgkmcnt(0)
	v_add_f32_e32 v43, v43, v44
	v_xor_b32_e32 v44, 2, v198
	v_exp_f32_e32 v50, v50
	v_exp_f32_e32 v54, v54
	v_cmp_lt_i32_e64 s[76:77], v44, v45
	v_mul_f32_e32 v49, 0xbfb8aa3b, v49
	v_mul_f32_e32 v48, 0xbfb8aa3b, v48
	v_cndmask_b32_e64 v44, v198, v44, s[76:77]
	v_lshlrev_b32_e32 v44, 2, v44
	v_add_f32_e32 v42, 1.0, v42
	v_add_f32_e32 v46, 1.0, v46
	v_exp_f32_e32 v49, v49
	v_exp_f32_e32 v48, v48
	v_mul_f32_e32 v57, 0xbfb8aa3b, v57
	v_mul_f32_e32 v56, 0xbfb8aa3b, v56
	ds_bpermute_b32 v44, v44, v43
	v_rcp_f32_e32 v52, v42
	v_rcp_f32_e32 v53, v46
	v_add_f32_e32 v50, 1.0, v50
	v_add_f32_e32 v54, 1.0, v54
	v_exp_f32_e32 v57, v57
	v_exp_f32_e32 v56, v56
	v_rcp_f32_e32 v58, v50
	v_rcp_f32_e32 v59, v54
	v_add_f32_e32 v49, 1.0, v49
	v_add_f32_e32 v48, 1.0, v48
	v_pk_mul_f32 v[46:47], v[52:53], s[30:31] op_sel_hi:[1,0]
	v_rcp_f32_e32 v52, v49
	v_rcp_f32_e32 v53, v48
	v_add_f32_e32 v57, 1.0, v57
	v_add_f32_e32 v56, 1.0, v56
	s_waitcnt lgkmcnt(0)
	v_add_f32_e32 v146, v43, v44
	v_xor_b32_e32 v43, 4, v198
	v_pk_mul_f32 v[54:55], v[58:59], s[30:31] op_sel_hi:[1,0]
	v_rcp_f32_e32 v58, v57
	v_rcp_f32_e32 v59, v56
	v_cmp_lt_i32_e64 s[76:77], v43, v45
	v_pk_mul_f32 v[48:49], v[52:53], s[30:31] op_sel_hi:[1,0]
	ds_read_b128 v[50:53], v111 offset:784
	v_cndmask_b32_e64 v43, v198, v43, s[76:77]
	v_lshlrev_b32_e32 v43, 2, v43
	ds_bpermute_b32 v147, v43, v146
	ds_read_b128 v[42:45], v111 offset:768
	v_pk_mul_f32 v[56:57], v[58:59], s[30:31] op_sel_hi:[1,0]
	ds_write_b128 v112, v[46:49]
	ds_write_b128 v112, v[54:57] offset:16
	s_waitcnt lgkmcnt(0)
	s_barrier
	ds_read2st64_b32 v[58:59], v159 offset1:1
	s_waitcnt lgkmcnt(0)
	v_add_f32_e32 v58, 0, v58
	v_add_f32_e32 v60, v58, v59
	ds_write2st64_b32 v159, v58, v60 offset1:1
	ds_read2st64_b32 v[58:59], v159 offset0:2 offset1:3
	s_waitcnt lgkmcnt(0)
	v_add_f32_e32 v58, v60, v58
	v_add_f32_e32 v60, v58, v59
	ds_write2st64_b32 v159, v58, v60 offset0:2 offset1:3
	ds_read2st64_b32 v[58:59], v159 offset0:4 offset1:5
	s_waitcnt lgkmcnt(0)
	v_add_f32_e32 v58, v60, v58
	v_add_f32_e32 v60, v58, v59
	ds_write2st64_b32 v159, v58, v60 offset0:4 offset1:5
	ds_read2st64_b32 v[58:59], v159 offset0:6 offset1:7
	s_waitcnt lgkmcnt(0)
	v_add_f32_e32 v58, v60, v58
	v_add_f32_e32 v59, v58, v59
	ds_write2st64_b32 v159, v58, v59 offset0:6 offset1:7
	ds_write_b32 v113, v59
	v_mov_b32_e32 v58, 0
	s_waitcnt lgkmcnt(0)
	s_barrier
	s_and_saveexec_b64 s[12:13], s[44:45]
	s_cbranch_execz .LBB0_215
	ds_read_b32 v58, v114
	s_waitcnt lgkmcnt(0)
	v_add_f32_e32 v58, 0, v58
.LBB0_215:
	s_or_b64 exec, exec, s[12:13]
	v_mov_b32_e32 v59, 0
	v_mov_b32_e32 v60, 0
	s_and_saveexec_b64 s[12:13], s[46:47]
	ds_read_b32 v60, v114 offset:256
	s_or_b64 exec, exec, s[12:13]
	s_and_saveexec_b64 s[12:13], s[48:49]
	ds_read_b32 v59, v114 offset:512
	s_or_b64 exec, exec, s[12:13]
	v_mov_b32_e32 v61, 0
	v_mov_b32_e32 v62, 0
	s_and_saveexec_b64 s[12:13], s[50:51]
	ds_read_b32 v62, v114 offset:768
	s_or_b64 exec, exec, s[12:13]
	s_and_saveexec_b64 s[12:13], s[52:53]
	ds_read_b32 v61, v114 offset:1024
	s_or_b64 exec, exec, s[12:13]
	v_mov_b32_e32 v63, 0
	v_mov_b32_e32 v64, 0
	s_and_saveexec_b64 s[12:13], s[54:55]
	ds_read_b32 v64, v114 offset:1280
	s_or_b64 exec, exec, s[12:13]
	s_and_saveexec_b64 s[12:13], s[56:57]
	ds_read_b32 v63, v114 offset:1536
	s_or_b64 exec, exec, s[12:13]
	s_waitcnt lgkmcnt(0)
	v_add_f32_e32 v58, v58, v60
	v_add_f32_e32 v58, v58, v59
	v_add_f32_e32 v58, v58, v62
	v_add_f32_e32 v58, v58, v61
	v_add_f32_e32 v60, v58, v64
	ds_read2st64_b32 v[58:59], v159 offset1:1
	v_add_f32_e32 v177, v60, v63
	ds_read2st64_b32 v[60:61], v159 offset0:2 offset1:3
	ds_read2st64_b32 v[62:63], v159 offset0:4 offset1:5
	ds_read2st64_b32 v[64:65], v159 offset0:6 offset1:7
	s_waitcnt lgkmcnt(3)
	v_add_f32_e32 v58, v177, v58
	v_add_f32_e32 v59, v177, v59
	ds_write2st64_b32 v159, v58, v59 offset1:1
	s_waitcnt lgkmcnt(3)
	v_add_f32_e32 v58, v177, v60
	v_add_f32_e32 v59, v177, v61
	ds_write2st64_b32 v159, v58, v59 offset0:2 offset1:3
	s_waitcnt lgkmcnt(3)
	v_add_f32_e32 v58, v177, v62
	v_add_f32_e32 v59, v177, v63
	ds_write2st64_b32 v159, v58, v59 offset0:4 offset1:5
	s_waitcnt lgkmcnt(3)
	v_add_f32_e32 v58, v177, v64
	v_add_f32_e32 v59, v177, v65
	ds_write2st64_b32 v159, v58, v59 offset0:6 offset1:7
	s_waitcnt lgkmcnt(0)
	s_barrier
; __device__ __forceinline__ float sigmoidf_(float x) { return __builtin_amdgcn_rcpf(1.0f + __expf(-x)); }
; template <bool PA> ...
;     ...
;                 for (int e = 0; e < 8; ++e) { kk[e] = kv[e] * cst[128 + c8 + e]; ss += kk[e] * kk[e]; }
;                 ss += __shfl_xor(ss, 1); ss += __shfl_xor(ss, 2); ss += __shfl_xor(ss, 4);
;                 const float inv = rsqrtf(fmaxf(ss, 1e-24f));
; #pragma unroll
;                 for (int e = 0; e < 8; ++e) { av[e] = sigmoidf_(aa[e]); lw[e] = -0.6065306597f * sigmoidf_(z[e]); kd[e] = kv[e] * (1.0f + (av[e] - 1.0f) * cst[192 + c8 + e]); kk[e] *= inv; bsum += rv[e] * kd[e] * cst[256 + c8 + e]; }
;                 bsum += __shfl_xor(bsum, 1); bsum += __shfl_xor(bsum, 2); bsum += __shfl_xor(bsum, 4);
;                 if (!PA && part == 0) beta[((size_t)d * SLAB + row) * 16 + head] = bsum;
;                 *(f32x4_t*)(cumb + j * 64 + c8) = (f32x4_t){lw[0], lw[1], lw[2], lw[3]}; *(f32x4_t*)(cumb + j * 64 + c8 + 4) = (f32x4_t){lw[4], lw[5], lw[6], lw[7]};
;             }
;             __syncthreads();
;             { const int c = tid & 63, sg = tid >> 6; float run = 0.f;
; #pragma unroll
;               for (int i = 0; i < 8; ++i) { run += cumb[(8 * sg + i) * 64 + c]; cumb[(8 * sg + i) * 64 + c] = run; }
;               segtot[sg * 64 + c] = run; }
;             __syncthreads();
;             { const int c = tid & 63, sg = tid >> 6; float off = 0.f;
; #pragma unroll
;               for (int s = 0; s < 7; ++s) off += (s < sg) ? segtot[s * 64 + c] : 0.f;
; #pragma unroll
;               for (int i = 0; i < 8; ++i) cumb[(8 * sg + i) * 64 + c] += off; }
;             __syncthreads();
;             {
;                 const f32x4_t c0 = *(const f32x4_t*)(cumb + j * 64 + c8), c1 = *(const f32x4_t*)(cumb + j * 64 + c8 + 4);
;                 float ah[8], bh[8], kh[8], rh[8];
; #pragma unroll
;                 for (int e = 0; e < 8; ++e) { const float cu = e < 4 ? c0[e & 3] : c1[e & 3]; const float Wt = __expf(cu), iW = __expf(-cu), Wm1 = __expf(cu - lw[e]);
;                     ah[e] = kk[e] * Wm1; bh[e] = -(kk[e] * av[e]) * iW; kh[e] = kd[e] * iW; rh[e] = rv[e] * Wt;
;                     if (j == 63) wc[c8 + e] = Wt; }
	ds_read_b128 v[58:61], v112
	ds_read_b128 v[62:65], v112 offset:16
	s_waitcnt lgkmcnt(1)
	v_mul_f32_e32 v177, 0x3fb8aa3b, v58
	v_exp_f32_e32 v177, v177
	s_and_saveexec_b64 s[12:13], s[42:43]
	ds_write_b32 v115, v177
	s_or_b64 exec, exec, s[12:13]
	v_mul_f32_e32 v178, 0x3fb8aa3b, v59
	v_exp_f32_e32 v178, v178
	s_and_saveexec_b64 s[12:13], s[42:43]
	ds_write_b32 v115, v178 offset:4
	s_or_b64 exec, exec, s[12:13]
	v_mul_f32_e32 v179, 0x3fb8aa3b, v60
	v_exp_f32_e32 v179, v179
	s_and_saveexec_b64 s[12:13], s[42:43]
	ds_write_b32 v115, v179 offset:8
	s_or_b64 exec, exec, s[12:13]
	v_mul_f32_e32 v180, 0x3fb8aa3b, v61
	v_exp_f32_e32 v180, v180
	s_and_saveexec_b64 s[12:13], s[42:43]
	ds_write_b32 v115, v180 offset:12
	s_or_b64 exec, exec, s[12:13]
	s_waitcnt lgkmcnt(0)
	v_mul_f32_e32 v181, 0x3fb8aa3b, v62
	v_exp_f32_e32 v181, v181
	s_and_saveexec_b64 s[12:13], s[42:43]
	ds_write_b32 v115, v181 offset:16
	s_or_b64 exec, exec, s[12:13]
	v_mul_f32_e32 v182, 0x3fb8aa3b, v63
	v_exp_f32_e32 v182, v182
	s_and_saveexec_b64 s[12:13], s[42:43]
	ds_write_b32 v115, v182 offset:20
	s_or_b64 exec, exec, s[12:13]
	v_mul_f32_e32 v183, 0x3fb8aa3b, v64
	v_exp_f32_e32 v183, v183
	s_and_saveexec_b64 s[12:13], s[42:43]
	ds_write_b32 v115, v183 offset:24
	s_or_b64 exec, exec, s[12:13]
	v_mul_f32_e32 v184, 0x3fb8aa3b, v65
	v_exp_f32_e32 v184, v184
	s_and_saveexec_b64 s[12:13], s[42:43]
	ds_write_b32 v115, v184 offset:28
	s_or_b64 exec, exec, s[12:13]
	v_add_f32_e32 v33, v33, v41
	v_mul_f32_e32 v33, 0xbfb8aa3b, v33
	v_add_f32_e32 v32, v32, v40
	v_exp_f32_e32 v33, v33
	v_mul_f32_e32 v32, 0xbfb8aa3b, v32
	v_exp_f32_e32 v32, v32
	v_add_f32_e32 v31, v31, v39
	v_add_f32_e32 v26, v26, v34
	v_add_f32_e32 v34, v146, v147
	v_mul_f32_e32 v31, 0xbfb8aa3b, v31
	v_add_f32_e32 v33, 1.0, v33
	v_max_f32_e32 v34, 0x179abe15, v34
	v_exp_f32_e32 v31, v31
	v_rcp_f32_e32 v33, v33
	v_sub_f32_e32 v39, v65, v57
	v_rsq_f32_e32 v34, v34
	v_add_f32_e32 v32, 1.0, v32
	v_mul_f32_e32 v39, 0x3fb8aa3b, v39
	v_add_f32_e32 v30, v30, v38
	v_rcp_f32_e32 v32, v32
	v_mul_f32_e32 v38, 0xbfb8aa3b, v65
	v_exp_f32_e32 v39, v39
	v_exp_f32_e32 v38, v38
	v_add_f32_e32 v28, v28, v36
	v_mul_f32_e32 v30, 0xbfb8aa3b, v30
	v_add_f32_e32 v31, 1.0, v31
	v_add_f32_e32 v36, -1.0, v33
	v_mul_f32_e32 v40, 0xbfb8aa3b, v64
	v_add_f32_e32 v29, v29, v37
	v_exp_f32_e32 v30, v30
	v_rcp_f32_e32 v31, v31
	v_fma_f32 v36, v36, v53, 1.0
	v_mul_f32_e32 v37, v176, v34
	v_exp_f32_e32 v40, v40
	v_mul_f32_e32 v36, v36, v175
	v_mul_f32_e32 v39, v37, v39
	v_mul_f32_e64 v33, v37, -v33
	v_add_f32_e32 v37, -1.0, v32
	v_mul_f32_e32 v29, 0xbfb8aa3b, v29
	v_mul_f32_e32 v33, v33, v38
	v_mul_f32_e32 v36, v36, v38
	v_fma_f32 v37, v37, v52, 1.0
	v_mul_f32_e32 v38, v174, v34
	v_sub_f32_e32 v41, v64, v56
	v_mul_f32_e32 v52, 0xbfb8aa3b, v63
	v_exp_f32_e32 v29, v29
	v_mul_f32_e32 v37, v37, v173
	v_mul_f32_e32 v41, 0x3fb8aa3b, v41
	v_mul_f32_e64 v32, v38, -v32
	v_exp_f32_e32 v52, v52
	v_sub_f32_e32 v53, v63, v55
	v_add_f32_e32 v30, 1.0, v30
	v_exp_f32_e32 v41, v41
	v_mul_f32_e32 v32, v32, v40
	v_mul_f32_e32 v37, v37, v40
	v_add_f32_e32 v40, -1.0, v31
	v_mul_f32_e32 v53, 0x3fb8aa3b, v53
	v_mul_f32_e32 v28, 0xbfb8aa3b, v28
	v_rcp_f32_e32 v30, v30
	v_fma_f32 v40, v40, v51, 1.0
	v_mul_f32_e32 v51, v172, v34
	v_exp_f32_e32 v53, v53
	v_exp_f32_e32 v28, v28
	v_mul_f32_e32 v40, v40, v171
	v_mul_f32_e64 v31, v51, -v31
	v_sub_f32_e32 v54, v62, v54
	v_add_f32_e32 v27, v27, v35
	v_add_f32_e32 v29, 1.0, v29
	v_and_b32_e32 v35, 0xffff0000, v25
	v_lshlrev_b32_e32 v25, 16, v25
	v_mul_f32_e32 v31, v31, v52
	v_mul_f32_e32 v40, v40, v52
	v_mul_f32_e32 v52, 0xbfb8aa3b, v62
	v_mul_f32_e32 v54, 0x3fb8aa3b, v54
	v_rcp_f32_e32 v29, v29
	v_mul_f32_e32 v41, v38, v41
	v_mul_f32_e32 v38, v183, v25
	v_and_b32_e32 v25, 0xffff0000, v24
	v_exp_f32_e32 v52, v52
	v_exp_f32_e32 v54, v54
	v_mul_f32_e32 v53, v51, v53
	v_mul_f32_e32 v51, v182, v25
	v_add_f32_e32 v25, -1.0, v30
	v_sub_f32_e32 v49, v61, v49
	v_add_f32_e32 v28, 1.0, v28
	v_fma_f32 v25, v25, v50, 1.0
	v_mul_f32_e32 v55, 0xbfb8aa3b, v61
	v_mul_f32_e32 v49, 0x3fb8aa3b, v49
	v_mul_f32_e32 v27, 0xbfb8aa3b, v27
	v_rcp_f32_e32 v28, v28
	v_mul_f32_e32 v25, v25, v169
	v_mul_f32_e32 v50, v170, v34
	v_exp_f32_e32 v55, v55
	v_exp_f32_e32 v49, v49
	v_exp_f32_e32 v27, v27
	v_mul_f32_e32 v54, v50, v54
	v_mul_f32_e64 v30, v50, -v30
	v_mul_f32_e32 v50, v25, v52
	v_add_f32_e32 v25, -1.0, v29
	v_lshlrev_b32_e32 v24, 16, v24
	v_fma_f32 v25, v25, v45, 1.0
	v_mul_f32_e32 v45, v168, v34
	v_mul_f32_e32 v30, v30, v52
	v_mul_f32_e32 v52, v181, v24
	v_and_b32_e32 v24, 0xffff0000, v23
	v_mul_f32_e32 v25, v25, v167
	v_mul_f32_e64 v29, v45, -v29
	v_sub_f32_e32 v48, v60, v48
	v_mul_f32_e32 v49, v45, v49
	v_mul_f32_e32 v29, v29, v55
	v_mul_f32_e32 v45, v25, v55
	v_mul_f32_e32 v55, v180, v24
	v_add_f32_e32 v24, -1.0, v28
	v_mul_f32_e32 v48, 0x3fb8aa3b, v48
	v_add_f32_e32 v27, 1.0, v27
	v_fma_f32 v24, v24, v44, 1.0
	v_mul_f32_e32 v44, 0xbfb8aa3b, v60
	v_exp_f32_e32 v48, v48
	v_rcp_f32_e32 v27, v27
	v_exp_f32_e32 v44, v44
	v_mul_f32_e32 v25, v166, v34
	v_mul_f32_e32 v24, v24, v165
	v_mul_f32_e32 v48, v25, v48
	v_mul_f32_e64 v25, v25, -v28
	v_sub_f32_e32 v47, v59, v47
	v_mul_f32_e32 v26, 0xbfb8aa3b, v26
	v_mul_f32_e32 v28, v25, v44
	v_mul_f32_e32 v44, v24, v44
	v_add_f32_e32 v24, -1.0, v27
	v_mul_f32_e32 v47, 0x3fb8aa3b, v47
	v_exp_f32_e32 v26, v26
	v_fma_f32 v24, v24, v43, 1.0
	v_mul_f32_e32 v43, 0xbfb8aa3b, v59
	v_exp_f32_e32 v47, v47
	v_exp_f32_e32 v43, v43
	v_mul_f32_e32 v25, v164, v34
	v_add_f32_e32 v26, 1.0, v26
	v_mul_f32_e32 v24, v24, v163
	v_mul_f32_e32 v47, v25, v47
	v_mul_f32_e64 v25, v25, -v27
	v_rcp_f32_e32 v26, v26
	v_mul_f32_e32 v27, v25, v43
; template <bool PA> ...
;     ...
;                 w.x = pk2(ah[0], ah[1]); w.y = pk2(ah[2], ah[3]); w.z = pk2(ah[4], ah[5]); w.w = pk2(ah[6], ah[7]); *(u32x4_t*)(MAT(0) + j * 72 + c8) = w;
;                 u32x4_t wb, wk;
;                 wb.x = pk2(bh[0], bh[1]); wb.y = pk2(bh[2], bh[3]); wb.z = pk2(bh[4], bh[5]); wb.w = pk2(bh[6], bh[7]); *(u32x4_t*)(MAT(1) + j * 72 + c8) = wb;
;                 wk.x = pk2(kh[0], kh[1]); wk.y = pk2(kh[2], kh[3]); wk.z = pk2(kh[4], kh[5]); wk.w = pk2(kh[6], kh[7]); *(u32x4_t*)(MAT(2) + j * 72 + c8) = wk;
;                 w.x = pk2(rh[0], rh[1]); w.y = pk2(rh[2], rh[3]); w.z = pk2(rh[4], rh[5]); w.w = pk2(rh[6], rh[7]); *(u32x4_t*)(MAT(3) + j * 72 + c8) = w;
;                 { const unsigned wba[4] = {wb.x, wb.y, wb.z, wb.w}, wka[4] = {wk.x, wk.y, wk.z, wk.w}, wva[4] = {vraw.x, vraw.y, vraw.z, vraw.w};
; #pragma unroll
;                   for (int q = 0; q < 4; ++q) { bf16* d4 = MAT(4) + (c8 + 2 * q) * 72 + j; bf16* d5 = MAT(5) + (c8 + 2 * q) * 72 + j; bf16* d6 = MAT(6) + (c8 + 2 * q) * 72 + j;
;                       d4[0] = (bf16)(wba[q] & 0xffffu); d4[72] = (bf16)(wba[q] >> 16); d5[0] = (bf16)(wka[q] & 0xffffu); d5[72] = (bf16)(wka[q] >> 16); d6[0] = (bf16)(wva[q] & 0xffffu); d6[72] = (bf16)(wva[q] >> 16); } }
;                 if (haveT) *(u32x4_t*)(MAT(9) + j * 72 + c8) = tld;
;                 st_rm(MAT(7), Sacc, mt, ntb, r16, kq);
;                 if (PA) st_rm(MAT(12), S2acc, mt, ntb, r16, kq);
;             }
;             __syncthreads();
;             f32x4_t Pacc[2], Tacc[2], Xacc[2], Yacc[2], tmp[2];
;             const f32x4_t z4 = (f32x4_t){0.f, 0.f, 0.f, 0.f};
;             Tacc[0] = z4; Tacc[1] = z4;
;             if (!haveT) {
;             Pacc[0] = z4; Pacc[1] = z4; mm2(Pacc, MAT(0), MAT(1), mt, ntb, r16, kq);
; #pragma unroll
;             for (int i = 0; i < 2; ++i)
; #pragma unroll
;                 for (int e = 0; e < 4; ++e) { const int t = 16 * mt + 4 * kq + e, s = 16 * (ntb + i) + r16; Pacc[i][e] = (s < t) ? Pacc[i][e] : 0.f; Tacc[i][e] = Pacc[i][e] + ((s == t) ? 1.f : 0.f); }
;             st_rm(MAT(8), Pacc, mt, ntb, r16, kq); st_tr(MAT(9), Pacc, mt, ntb, r16, kq);
;             }
;             tmp[0] = z4; tmp[1] = z4; mm2(tmp, MAT(0), MAT(2), mt, ntb, r16, kq);
; #pragma unroll
;             for (int i = 0; i < 2; ++i)
; #pragma unroll
	v_mul_f32_e32 v43, v24, v43
	v_mul_f32_e32 v24, v162, v34
	v_sub_f32_e32 v34, v58, v46
	v_mul_f32_e32 v34, 0x3fb8aa3b, v34
	v_lshlrev_b32_e32 v23, 16, v23
	v_mul_f32_e32 v25, 0xbfb8aa3b, v58
	v_exp_f32_e32 v34, v34
	v_mul_f32_e32 v56, v179, v23
	v_and_b32_e32 v23, 0xffff0000, v22
	v_exp_f32_e32 v25, v25
	v_mul_f32_e32 v57, v178, v23
	v_add_f32_e32 v23, -1.0, v26
	v_fma_f32 v23, v23, v42, 1.0
	v_lshlrev_b32_e32 v22, 16, v22
	v_mul_f32_e32 v23, v23, v161
	v_mul_f32_e32 v34, v24, v34
	v_mul_f32_e64 v24, v24, -v26
	v_mul_f32_e32 v35, v184, v35
	v_mul_f32_e32 v26, v24, v25
	v_mul_f32_e32 v42, v23, v25
	v_mul_f32_e32 v46, v177, v22
	v_cvt_pk_bf16_f32 v22, v34, v47
	v_cvt_pk_bf16_f32 v23, v48, v49
	v_cvt_pk_bf16_f32 v24, v54, v53
	v_cvt_pk_bf16_f32 v25, v41, v39
	ds_write_b128 v68, v[22:25]
	v_cvt_pk_bf16_f32 v22, v26, v27
	v_cvt_pk_bf16_f32 v23, v28, v29
	v_cvt_pk_bf16_f32 v24, v30, v31
	v_cvt_pk_bf16_f32 v25, v32, v33
	v_cvt_pk_bf16_f32 v26, v42, v43
	v_cvt_pk_bf16_f32 v27, v44, v45
	v_cvt_pk_bf16_f32 v28, v50, v40
	v_cvt_pk_bf16_f32 v29, v37, v36
	v_cvt_pk_bf16_f32 v30, v46, v57
	v_cvt_pk_bf16_f32 v31, v56, v55
	v_cvt_pk_bf16_f32 v32, v52, v51
	v_cvt_pk_bf16_f32 v33, v38, v35
	ds_write_b128 v68, v[22:25] offset:9216
	ds_write_b128 v68, v[26:29] offset:18432
	ds_write_b128 v68, v[30:33] offset:27648
	ds_write_b16 v154, v22 offset:36864
	ds_write_b16_d16_hi v154, v22 offset:37008
	ds_write_b16 v154, v26 offset:46080
	ds_write_b16_d16_hi v154, v26 offset:46224
	s_nop 0
	ds_write_b16 v154, v18 offset:55296
	ds_write_b16_d16_hi v154, v18 offset:55440
	ds_write_b16 v154, v23 offset:37152
	ds_write_b16_d16_hi v154, v23 offset:37296
	ds_write_b16 v154, v27 offset:46368
	ds_write_b16_d16_hi v154, v27 offset:46512
	ds_write_b16 v154, v19 offset:55584
	ds_write_b16_d16_hi v154, v19 offset:55728
	ds_write_b16 v154, v24 offset:37440
	ds_write_b16_d16_hi v154, v24 offset:37584
	ds_write_b16 v154, v28 offset:46656
	ds_write_b16_d16_hi v154, v28 offset:46800
	ds_write_b16 v154, v20 offset:55872
	ds_write_b16_d16_hi v154, v20 offset:56016
	ds_write_b16 v154, v25 offset:37728
	ds_write_b16_d16_hi v154, v25 offset:37872
	ds_write_b16 v154, v29 offset:46944
	ds_write_b16_d16_hi v154, v29 offset:47088
	ds_write_b16 v154, v21 offset:56160
	ds_write_b16_d16_hi v154, v21 offset:56304
	v_cvt_pk_bf16_f32 v18, v2, v3
	v_cvt_pk_bf16_f32 v19, v4, v5
	ds_write_b16 v116, v18 offset:64512
	ds_write_b16_d16_hi v116, v18 offset:64656
	ds_write_b16 v116, v19 offset:64800
	ds_write_b16_d16_hi v116, v19 offset:64944
	v_cvt_pk_bf16_f32 v18, v6, v7
	v_cvt_pk_bf16_f32 v0, v8, v0
	ds_write_b16 v116, v18 offset:64544
	ds_write_b16_d16_hi v116, v18 offset:64688
	ds_write_b16 v116, v0 offset:64832
	ds_write_b16_d16_hi v116, v0 offset:64976
	v_cvt_pk_bf16_f32 v0, v10, v11
	v_cvt_pk_bf16_f32 v18, v12, v13
	ds_write_b16 v117, v0
	ds_write_b16_d16_hi v117, v0 offset:144
	ds_write_b16 v117, v18 offset:288
	ds_write_b16_d16_hi v117, v18 offset:432
	v_cvt_pk_bf16_f32 v0, v14, v15
	v_cvt_pk_bf16_f32 v18, v16, v17
	ds_write_b16 v117, v0 offset:32
	ds_write_b16_d16_hi v117, v0 offset:176
	ds_write_b16 v117, v18 offset:320
	ds_write_b16_d16_hi v117, v18 offset:464
	s_waitcnt lgkmcnt(0)
	s_barrier
	ds_read_b128 v[18:21], v69
	ds_read_b128 v[22:25], v118 offset:9216
	ds_read_b128 v[26:29], v118 offset:11520
	s_waitcnt lgkmcnt(1)
	v_mfma_f32_16x16x32_bf16 v[22:25], v[18:21], v[22:25], 0
	s_waitcnt lgkmcnt(0)
	v_mfma_f32_16x16x32_bf16 v[18:21], v[18:21], v[26:29], 0
	ds_read_b128 v[26:29], v69 offset:64
	ds_read_b128 v[30:33], v118 offset:9280
	s_waitcnt lgkmcnt(0)
	v_mfma_f32_16x16x32_bf16 v[22:25], v[26:29], v[30:33], v[22:25]
	ds_read_b128 v[30:33], v118 offset:11584
	s_waitcnt lgkmcnt(0)
	v_mfma_f32_16x16x32_bf16 v[18:21], v[26:29], v[30:33], v[18:21]
	s_nop 4
	v_cndmask_b32_e64 v0, 0, v22, s[58:59]
	v_cndmask_b32_e64 v22, v23, 0, s[60:61]
	v_cndmask_b32_e64 v23, 0, v24, s[62:63]
	v_cndmask_b32_e64 v24, 0, v25, s[64:65]
	v_cndmask_b32_e64 v25, 0, v18, s[66:67]
	v_cndmask_b32_e64 v26, v19, 0, s[68:69]
	v_cndmask_b32_e64 v27, 0, v20, s[70:71]
	v_cndmask_b32_e64 v21, 0, v21, s[72:73]
	v_add_f32_e32 v65, v143, v21
	v_cvt_pk_bf16_f32 v18, v0, v22
	v_cvt_pk_bf16_f32 v20, v25, v26
	v_cvt_pk_bf16_f32 v21, v27, v21
	v_cvt_pk_bf16_f32 v19, v23, v24
	ds_write_b16 v119, v18
	ds_write_b16_d16_hi v119, v18 offset:144
	ds_write_b16 v119, v19 offset:288
	ds_write_b16_d16_hi v119, v19 offset:432
	ds_write_b16 v119, v20 offset:32
	ds_write_b16_d16_hi v119, v20 offset:176
	ds_write_b16 v119, v21 offset:320
	ds_write_b16_d16_hi v119, v21 offset:464
	ds_write_b64 v120, v[18:19]
	ds_write_b64 v120, v[20:21] offset:2304
	v_add_f32_e32 v59, v137, v22
	v_add_f32_e32 v60, v138, v23
	v_add_f32_e32 v61, v139, v24
	v_add_f32_e32 v62, v140, v25
	v_add_f32_e32 v63, v141, v26
	v_add_f32_e32 v64, v142, v27
	ds_read_b128 v[18:21], v69
	ds_read_b128 v[22:25], v118 offset:18432
	ds_read_b128 v[26:29], v118 offset:20736
	s_waitcnt lgkmcnt(1)
	v_mfma_f32_16x16x32_bf16 v[22:25], v[18:21], v[22:25], 0
	v_add_f32_e32 v58, v136, v0
	s_waitcnt lgkmcnt(0)
	v_mfma_f32_16x16x32_bf16 v[18:21], v[18:21], v[26:29], 0
	ds_read_b128 v[26:29], v69 offset:64
	ds_read_b128 v[30:33], v118 offset:18496
	s_waitcnt lgkmcnt(0)
	v_mfma_f32_16x16x32_bf16 v[22:25], v[26:29], v[30:33], v[22:25]
	ds_read_b128 v[30:33], v118 offset:20800
	s_waitcnt lgkmcnt(0)
	v_mfma_f32_16x16x32_bf16 v[18:21], v[26:29], v[30:33], v[18:21]
	s_nop 4
	v_cndmask_b32_e64 v0, 0, v22, s[58:59]
	v_cndmask_b32_e64 v22, v23, 0, s[60:61]
	v_cndmask_b32_e64 v23, 0, v24, s[62:63]
	v_cndmask_b32_e64 v24, 0, v25, s[64:65]
	v_cndmask_b32_e64 v18, 0, v18, s[66:67]
	v_cndmask_b32_e64 v19, v19, 0, s[68:69]
	v_cvt_pk_bf16_f32 v0, v0, v22
	v_cndmask_b32_e64 v20, 0, v20, s[70:71]
	v_cndmask_b32_e64 v21, 0, v21, s[72:73]
	v_cvt_pk_bf16_f32 v22, v23, v24
	ds_write_b16 v121, v0
	ds_write_b16_d16_hi v121, v0 offset:144
	ds_write_b16 v121, v22 offset:288
	ds_write_b16_d16_hi v121, v22 offset:432
	v_cvt_pk_bf16_f32 v0, v18, v19
	v_cvt_pk_bf16_f32 v18, v20, v21
	ds_write_b16 v121, v0 offset:32
	ds_write_b16_d16_hi v121, v0 offset:176
	ds_write_b16 v121, v18 offset:320
	ds_write_b16_d16_hi v121, v18 offset:464
	ds_read_b128 v[22:25], v69
	ds_read_b128 v[42:45], v122
	ds_read_b128 v[46:49], v122 offset:2304
	ds_read_b128 v[18:21], v69 offset:64
	ds_read_b128 v[54:57], v122 offset:64
	ds_read_b128 v[50:53], v122 offset:2368
	ds_read_b128 v[38:41], v118 offset:64512
	ds_read_b128 v[34:37], v123
	ds_read_b128 v[30:33], v118 offset:64576
	ds_read_b128 v[26:29], v124
	s_waitcnt lgkmcnt(0)
	s_barrier
; template <bool PA> ...
;     ...
;             tmp[0] = z4; tmp[1] = z4; mm2(tmp, MAT(8), MAT(9), mt, ntb, r16, kq);
;             st_rm(MAT(0), tmp, mt, ntb, r16, kq); st_tr(MAT(1), tmp, mt, ntb, r16, kq); st_rm(MAT(2), Tacc, mt, ntb, r16, kq);
;             __syncthreads();
; #pragma unroll
;             for (int i = 1; i <= 5; ++i) {
;                 bf16* Pc = (i & 1) ? MAT(0) : MAT(8); bf16* PcT = (i & 1) ? MAT(1) : MAT(9); bf16* Pn = (i & 1) ? MAT(8) : MAT(0); bf16* PnT = (i & 1) ? MAT(9) : MAT(1);
;                 bf16* Tc = (i & 1) ? MAT(2) : MAT(3); bf16* Tn = (i & 1) ? MAT(3) : MAT(2);
;                 mm2(Tacc, Tc, PcT, mt, ntb, r16, kq);
;                 if (i < 5) { tmp[0] = z4; tmp[1] = z4; mm2(tmp, Pc, PcT, mt, ntb, r16, kq); st_rm(Pn, tmp, mt, ntb, r16, kq); st_tr(PnT, tmp, mt, ntb, r16, kq); }
;                 st_rm(Tn, Tacc, mt, ntb, r16, kq);
;                 __syncthreads();
;             }
	ds_read_b128 v[162:165], v125
	ds_read_b128 v[166:169], v126
	ds_read_b128 v[170:173], v126 offset:2304
	s_waitcnt lgkmcnt(1)
	v_mfma_f32_16x16x32_bf16 v[166:169], v[162:165], v[166:169], 0
	v_cvt_pk_bf16_f32 v0, v58, v59
	s_waitcnt lgkmcnt(0)
	v_mfma_f32_16x16x32_bf16 v[162:165], v[162:165], v[170:173], 0
	ds_read_b128 v[170:173], v125 offset:64
	ds_read_b128 v[174:177], v126 offset:64
	s_waitcnt lgkmcnt(0)
	v_mfma_f32_16x16x32_bf16 v[166:169], v[170:173], v[174:177], v[166:169]
	ds_read_b128 v[174:177], v126 offset:2368
	s_waitcnt lgkmcnt(0)
	v_mfma_f32_16x16x32_bf16 v[162:165], v[170:173], v[174:177], v[162:165]
	s_nop 4
	v_cvt_pk_bf16_f32 v146, v166, v167
	v_cvt_pk_bf16_f32 v147, v168, v169
	ds_write_b16 v116, v146
	ds_write_b16_d16_hi v116, v146 offset:144
	ds_write_b16 v116, v147 offset:288
	ds_write_b16_d16_hi v116, v147 offset:432
	v_cvt_pk_bf16_f32 v162, v162, v163
	v_cvt_pk_bf16_f32 v163, v164, v165
	ds_write_b16 v116, v162 offset:32
	ds_write_b16_d16_hi v116, v162 offset:176
	ds_write_b16 v116, v163 offset:320
	ds_write_b16_d16_hi v116, v163 offset:464
	ds_write_b64 v127, v[146:147] offset:9216
	ds_write_b64 v127, v[162:163] offset:11520
	v_cvt_pk_bf16_f32 v146, v60, v61
	ds_write_b16 v116, v0 offset:18432
	ds_write_b16_d16_hi v116, v0 offset:18576
	ds_write_b16 v116, v146 offset:18720
	ds_write_b16_d16_hi v116, v146 offset:18864
	v_cvt_pk_bf16_f32 v0, v62, v63
	v_cvt_pk_bf16_f32 v146, v64, v65
	ds_write_b16 v116, v0 offset:18464
	ds_write_b16_d16_hi v116, v0 offset:18608
	ds_write_b16 v116, v146 offset:18752
	ds_write_b16_d16_hi v116, v146 offset:18896
	s_waitcnt lgkmcnt(0)
	s_barrier
	ds_read_b128 v[162:165], v69 offset:18432
	ds_read_b128 v[166:169], v118 offset:9216
	ds_read_b128 v[170:173], v118 offset:11520
	s_waitcnt lgkmcnt(1)
	v_mfma_f32_16x16x32_bf16 v[58:61], v[162:165], v[166:169], v[58:61]
	s_waitcnt lgkmcnt(0)
	v_mfma_f32_16x16x32_bf16 v[62:65], v[162:165], v[170:173], v[62:65]
	ds_read_b128 v[162:165], v69 offset:18496
	ds_read_b128 v[174:177], v118 offset:9280
	ds_read_b128 v[178:181], v118 offset:11584
	s_waitcnt lgkmcnt(1)
	v_mfma_f32_16x16x32_bf16 v[58:61], v[162:165], v[174:177], v[58:61]
	s_waitcnt lgkmcnt(0)
	v_mfma_f32_16x16x32_bf16 v[62:65], v[162:165], v[178:181], v[62:65]
	ds_read_b128 v[162:165], v69
	s_nop 4
	v_cvt_pk_bf16_f32 v0, v58, v59
	s_waitcnt lgkmcnt(0)
	v_mfma_f32_16x16x32_bf16 v[166:169], v[162:165], v[166:169], 0
	v_mfma_f32_16x16x32_bf16 v[162:165], v[162:165], v[170:173], 0
	ds_read_b128 v[170:173], v69 offset:64
	s_waitcnt lgkmcnt(0)
	v_mfma_f32_16x16x32_bf16 v[166:169], v[170:173], v[174:177], v[166:169]
	s_nop 7
	v_cvt_pk_bf16_f32 v146, v166, v167
	v_mfma_f32_16x16x32_bf16 v[162:165], v[170:173], v[178:181], v[162:165]
	v_cvt_pk_bf16_f32 v147, v168, v169
	ds_write_b16 v155, v146
	ds_write_b16_d16_hi v155, v146 offset:144
	ds_write_b16 v155, v147 offset:288
	ds_write_b16_d16_hi v155, v147 offset:432
	s_nop 2
	v_cvt_pk_bf16_f32 v162, v162, v163
	v_cvt_pk_bf16_f32 v163, v164, v165
	ds_write_b16 v155, v162 offset:32
	ds_write_b16_d16_hi v155, v162 offset:176
	ds_write_b16 v155, v163 offset:320
	ds_write_b16_d16_hi v155, v163 offset:464
	ds_write_b64 v120, v[146:147]
	ds_write_b64 v120, v[162:163] offset:2304
	v_cvt_pk_bf16_f32 v146, v60, v61
	ds_write_b16 v156, v0 offset:27648
	ds_write_b16_d16_hi v156, v0 offset:27792
	ds_write_b16 v156, v146 offset:27936
	ds_write_b16_d16_hi v156, v146 offset:28080
	v_cvt_pk_bf16_f32 v0, v62, v63
	v_cvt_pk_bf16_f32 v146, v64, v65
	ds_write_b16 v156, v0 offset:27680
	ds_write_b16_d16_hi v156, v0 offset:27824
	ds_write_b16 v156, v146 offset:27968
	ds_write_b16_d16_hi v156, v146 offset:28112
	s_waitcnt lgkmcnt(0)
	s_barrier
	ds_read_b128 v[162:165], v69 offset:27648
	ds_read_b128 v[166:169], v126
	ds_read_b128 v[170:173], v126 offset:2304
	s_waitcnt lgkmcnt(1)
	v_mfma_f32_16x16x32_bf16 v[58:61], v[162:165], v[166:169], v[58:61]
	s_waitcnt lgkmcnt(0)
	v_mfma_f32_16x16x32_bf16 v[62:65], v[162:165], v[170:173], v[62:65]
	ds_read_b128 v[162:165], v69 offset:27712
	ds_read_b128 v[174:177], v126 offset:64
	ds_read_b128 v[178:181], v126 offset:2368
	s_waitcnt lgkmcnt(1)
	v_mfma_f32_16x16x32_bf16 v[58:61], v[162:165], v[174:177], v[58:61]
	s_waitcnt lgkmcnt(0)
	v_mfma_f32_16x16x32_bf16 v[62:65], v[162:165], v[178:181], v[62:65]
	ds_read_b128 v[162:165], v125
	s_nop 4
	v_cvt_pk_bf16_f32 v0, v58, v59
	s_waitcnt lgkmcnt(0)
	v_mfma_f32_16x16x32_bf16 v[166:169], v[162:165], v[166:169], 0
	v_mfma_f32_16x16x32_bf16 v[162:165], v[162:165], v[170:173], 0
	ds_read_b128 v[170:173], v125 offset:64
	s_waitcnt lgkmcnt(0)
	v_mfma_f32_16x16x32_bf16 v[166:169], v[170:173], v[174:177], v[166:169]
	s_nop 7
	v_cvt_pk_bf16_f32 v146, v166, v167
	v_mfma_f32_16x16x32_bf16 v[162:165], v[170:173], v[178:181], v[162:165]
	v_cvt_pk_bf16_f32 v147, v168, v169
	ds_write_b16 v156, v146
	ds_write_b16_d16_hi v156, v146 offset:144
	ds_write_b16 v156, v147 offset:288
	ds_write_b16_d16_hi v156, v147 offset:432
	s_nop 2
	v_cvt_pk_bf16_f32 v162, v162, v163
	v_cvt_pk_bf16_f32 v163, v164, v165
	ds_write_b16 v156, v162 offset:32
	ds_write_b16_d16_hi v156, v162 offset:176
	ds_write_b16 v156, v163 offset:320
	ds_write_b16_d16_hi v156, v163 offset:464
	ds_write_b64 v127, v[146:147] offset:9216
	ds_write_b64 v127, v[162:163] offset:11520
	v_cvt_pk_bf16_f32 v146, v60, v61
	ds_write_b16 v156, v0 offset:18432
	ds_write_b16_d16_hi v156, v0 offset:18576
	ds_write_b16 v156, v146 offset:18720
	ds_write_b16_d16_hi v156, v146 offset:18864
	v_cvt_pk_bf16_f32 v0, v62, v63
	v_cvt_pk_bf16_f32 v146, v64, v65
	ds_write_b16 v156, v0 offset:18464
	ds_write_b16_d16_hi v156, v0 offset:18608
	ds_write_b16 v156, v146 offset:18752
	ds_write_b16_d16_hi v156, v146 offset:18896
	s_waitcnt lgkmcnt(0)
	s_barrier
; template <bool PA> ...
;     ...
;             Xacc[0] = z4; Xacc[1] = z4; mm2(Xacc, MAT(0), MAT(7), mt, ntb, r16, kq);
;             Yacc[0] = z4; Yacc[1] = z4; if (!PA) mm2(Yacc, MAT(3), MAT(7), mt, ntb, r16, kq);
;             __syncthreads();
;             if (!haveT) {
;             tmp[0] = z4; tmp[1] = z4; mm2(tmp, MAT(8), MAT(9), mt, ntb, r16, kq);
;             st_rm(MAT(0), tmp, mt, ntb, r16, kq); st_tr(MAT(1), tmp, mt, ntb, r16, kq); st_rm(MAT(2), Tacc, mt, ntb, r16, kq);
;             __syncthreads();
; #pragma unroll
;             for (int i = 1; i <= 5; ++i) {
;                 bf16* Pc = (i & 1) ? MAT(0) : MAT(8); bf16* PcT = (i & 1) ? MAT(1) : MAT(9); bf16* Pn = (i & 1) ? MAT(8) : MAT(0); bf16* PnT = (i & 1) ? MAT(9) : MAT(1);
;                 bf16* Tc = (i & 1) ? MAT(2) : MAT(3); bf16* Tn = (i & 1) ? MAT(3) : MAT(2);
;                 mm2(Tacc, Tc, PcT, mt, ntb, r16, kq);
;                 if (i < 5) { tmp[0] = z4; tmp[1] = z4; mm2(tmp, Pc, PcT, mt, ntb, r16, kq); st_rm(Pn, tmp, mt, ntb, r16, kq); st_tr(PnT, tmp, mt, ntb, r16, kq); }
;                 st_rm(Tn, Tacc, mt, ntb, r16, kq);
;                 __syncthreads();
;             }
;             }
;             if (PA && tlow) *(u32x4_t*)(tbuf + ((size_t)strm * NCHA + p) * 2304 + tunit * 8) = *(const u32x4_t*)(MAT(3) + j * 72 + c8);
	ds_read_b128 v[162:165], v69 offset:18432
	ds_read_b128 v[166:169], v118 offset:9216
	ds_read_b128 v[170:173], v118 offset:11520
	s_waitcnt lgkmcnt(1)
	v_mfma_f32_16x16x32_bf16 v[58:61], v[162:165], v[166:169], v[58:61]
	s_waitcnt lgkmcnt(0)
	v_mfma_f32_16x16x32_bf16 v[62:65], v[162:165], v[170:173], v[62:65]
	ds_read_b128 v[162:165], v69 offset:18496
	ds_read_b128 v[174:177], v118 offset:9280
	ds_read_b128 v[178:181], v118 offset:11584
	s_waitcnt lgkmcnt(1)
	v_mfma_f32_16x16x32_bf16 v[58:61], v[162:165], v[174:177], v[58:61]
	s_waitcnt lgkmcnt(0)
	v_mfma_f32_16x16x32_bf16 v[62:65], v[162:165], v[178:181], v[62:65]
	ds_read_b128 v[162:165], v69
	s_nop 4
	v_cvt_pk_bf16_f32 v0, v58, v59
	s_waitcnt lgkmcnt(0)
	v_mfma_f32_16x16x32_bf16 v[166:169], v[162:165], v[166:169], 0
	v_mfma_f32_16x16x32_bf16 v[162:165], v[162:165], v[170:173], 0
	ds_read_b128 v[170:173], v69 offset:64
	s_waitcnt lgkmcnt(0)
	v_mfma_f32_16x16x32_bf16 v[166:169], v[170:173], v[174:177], v[166:169]
	s_nop 7
	v_cvt_pk_bf16_f32 v146, v166, v167
	v_mfma_f32_16x16x32_bf16 v[162:165], v[170:173], v[178:181], v[162:165]
	v_cvt_pk_bf16_f32 v147, v168, v169
	ds_write_b16 v155, v146
	ds_write_b16_d16_hi v155, v146 offset:144
	ds_write_b16 v155, v147 offset:288
	ds_write_b16_d16_hi v155, v147 offset:432
	s_nop 2
	v_cvt_pk_bf16_f32 v162, v162, v163
	v_cvt_pk_bf16_f32 v163, v164, v165
	ds_write_b16 v155, v162 offset:32
	ds_write_b16_d16_hi v155, v162 offset:176
	ds_write_b16 v155, v163 offset:320
	ds_write_b16_d16_hi v155, v163 offset:464
	ds_write_b64 v120, v[146:147]
	ds_write_b64 v120, v[162:163] offset:2304
	v_cvt_pk_bf16_f32 v146, v60, v61
	ds_write_b16 v156, v0 offset:27648
	ds_write_b16_d16_hi v156, v0 offset:27792
	ds_write_b16 v156, v146 offset:27936
	ds_write_b16_d16_hi v156, v146 offset:28080
	v_cvt_pk_bf16_f32 v0, v62, v63
	v_cvt_pk_bf16_f32 v146, v64, v65
	ds_write_b16 v156, v0 offset:27680
	ds_write_b16_d16_hi v156, v0 offset:27824
	ds_write_b16 v156, v146 offset:27968
	ds_write_b16_d16_hi v156, v146 offset:28112
	s_waitcnt lgkmcnt(0)
	s_barrier
	ds_read_b128 v[162:165], v69 offset:27648
	ds_read_b128 v[166:169], v126
	ds_read_b128 v[170:173], v126 offset:2304
	s_waitcnt lgkmcnt(1)
	v_mfma_f32_16x16x32_bf16 v[58:61], v[162:165], v[166:169], v[58:61]
	s_waitcnt lgkmcnt(0)
	v_mfma_f32_16x16x32_bf16 v[62:65], v[162:165], v[170:173], v[62:65]
	ds_read_b128 v[162:165], v69 offset:27712
	ds_read_b128 v[174:177], v126 offset:64
	ds_read_b128 v[178:181], v126 offset:2368
	s_waitcnt lgkmcnt(1)
	v_mfma_f32_16x16x32_bf16 v[58:61], v[162:165], v[174:177], v[58:61]
	s_waitcnt lgkmcnt(0)
	v_mfma_f32_16x16x32_bf16 v[62:65], v[162:165], v[178:181], v[62:65]
	ds_read_b128 v[162:165], v125
	s_nop 4
	v_cvt_pk_bf16_f32 v0, v58, v59
	s_waitcnt lgkmcnt(0)
	v_mfma_f32_16x16x32_bf16 v[166:169], v[162:165], v[166:169], 0
	v_mfma_f32_16x16x32_bf16 v[162:165], v[162:165], v[170:173], 0
	ds_read_b128 v[170:173], v125 offset:64
	s_waitcnt lgkmcnt(0)
	v_mfma_f32_16x16x32_bf16 v[166:169], v[170:173], v[174:177], v[166:169]
	s_nop 7
	v_cvt_pk_bf16_f32 v146, v166, v167
	v_mfma_f32_16x16x32_bf16 v[162:165], v[170:173], v[178:181], v[162:165]
	v_cvt_pk_bf16_f32 v147, v168, v169
	ds_write_b16 v156, v146
	ds_write_b16_d16_hi v156, v146 offset:144
	ds_write_b16 v156, v147 offset:288
	ds_write_b16_d16_hi v156, v147 offset:432
	s_nop 2
	v_cvt_pk_bf16_f32 v162, v162, v163
	v_cvt_pk_bf16_f32 v163, v164, v165
	ds_write_b16 v156, v162 offset:32
	ds_write_b16_d16_hi v156, v162 offset:176
	ds_write_b16 v156, v163 offset:320
	ds_write_b16_d16_hi v156, v163 offset:464
	ds_write_b64 v127, v[146:147] offset:9216
	ds_write_b64 v127, v[162:163] offset:11520
	v_cvt_pk_bf16_f32 v146, v60, v61
	ds_write_b16 v156, v0 offset:18432
	ds_write_b16_d16_hi v156, v0 offset:18576
	ds_write_b16 v156, v146 offset:18720
	ds_write_b16_d16_hi v156, v146 offset:18864
	v_cvt_pk_bf16_f32 v0, v62, v63
	v_cvt_pk_bf16_f32 v146, v64, v65
	ds_write_b16 v156, v0 offset:18464
	ds_write_b16_d16_hi v156, v0 offset:18608
	ds_write_b16 v156, v146 offset:18752
	ds_write_b16_d16_hi v156, v146 offset:18896
	s_waitcnt lgkmcnt(0)
	s_barrier
	ds_read_b128 v[162:165], v69 offset:18432
	ds_read_b128 v[166:169], v118 offset:9216
	s_waitcnt lgkmcnt(0)
	v_mfma_f32_16x16x32_bf16 v[58:61], v[162:165], v[166:169], v[58:61]
	ds_read_b128 v[166:169], v118 offset:11520
	s_waitcnt lgkmcnt(0)
	v_mfma_f32_16x16x32_bf16 v[62:65], v[162:165], v[166:169], v[62:65]
	ds_read_b128 v[162:165], v69 offset:18496
	ds_read_b128 v[166:169], v118 offset:9280
	s_waitcnt lgkmcnt(0)
	v_mfma_f32_16x16x32_bf16 v[58:61], v[162:165], v[166:169], v[58:61]
	ds_read_b128 v[166:169], v118 offset:11584
	s_waitcnt lgkmcnt(0)
	v_mfma_f32_16x16x32_bf16 v[62:65], v[162:165], v[166:169], v[62:65]
	s_nop 4
	v_cvt_pk_bf16_f32 v0, v58, v59
	v_cvt_pk_bf16_f32 v58, v60, v61
	ds_write_b16 v156, v0 offset:27648
	ds_write_b16_d16_hi v156, v0 offset:27792
	ds_write_b16 v156, v58 offset:27936
	ds_write_b16_d16_hi v156, v58 offset:28080
	v_cvt_pk_bf16_f32 v0, v62, v63
	v_cvt_pk_bf16_f32 v58, v64, v65
	ds_write_b16 v156, v0 offset:27680
	ds_write_b16_d16_hi v156, v0 offset:27824
	ds_write_b16 v156, v58 offset:27968
	ds_write_b16_d16_hi v156, v58 offset:28112
	v_mfma_f32_16x16x32_bf16 v[42:45], v[22:25], v[42:45], 0
	s_waitcnt lgkmcnt(0)
	s_barrier
	v_mfma_f32_16x16x32_bf16 v[58:61], v[22:25], v[46:49], 0
	v_mfma_f32_16x16x32_bf16 v[38:41], v[22:25], v[38:41], 0
	v_mfma_f32_16x16x32_bf16 v[34:37], v[22:25], v[34:37], 0
	v_mfma_f32_16x16x32_bf16 v[46:49], v[18:21], v[54:57], v[42:45]
	v_mfma_f32_16x16x32_bf16 v[42:45], v[18:21], v[50:53], v[58:61]
	v_mfma_f32_16x16x32_bf16 v[22:25], v[18:21], v[30:33], v[38:41]
	v_mfma_f32_16x16x32_bf16 v[18:21], v[18:21], v[26:29], v[34:37]
	s_and_saveexec_b64 s[12:13], vcc
	s_cbranch_execz .LBB0_245
	ds_read_b128 v[26:29], v68 offset:27648
	s_waitcnt lgkmcnt(0)
	global_store_dwordx4 v[100:101], v[26:29], off

; __global__ void __launch_bounds__(512, 2) fwd_mega(Args a_) {
	.amdhsa_kernel _Z8fwd_mega4Args
		.amdhsa_group_segment_fixed_size 0
		.amdhsa_private_segment_fixed_size 0
		.amdhsa_kernarg_size 528
		.amdhsa_user_sgpr_count 2
		.amdhsa_user_sgpr_dispatch_ptr 0
		.amdhsa_user_sgpr_queue_ptr 0
		.amdhsa_user_sgpr_kernarg_segment_ptr 1
		.amdhsa_user_sgpr_dispatch_id 0
		.amdhsa_user_sgpr_kernarg_preload_length 0
		.amdhsa_user_sgpr_kernarg_preload_offset 0
		.amdhsa_user_sgpr_private_segment_size 0
		.amdhsa_uses_dynamic_stack 0
		.amdhsa_enable_private_segment 0
		.amdhsa_system_sgpr_workgroup_id_x 1
		.amdhsa_system_sgpr_workgroup_id_y 0
		.amdhsa_system_sgpr_workgroup_id_z 0
		.amdhsa_system_sgpr_workgroup_info 0
		.amdhsa_system_vgpr_workitem_id 2
		.amdhsa_next_free_vgpr 256
		.amdhsa_next_free_sgpr 100
		.amdhsa_accum_offset 256
		.amdhsa_reserve_vcc 1
		.amdhsa_float_round_mode_32 0
		.amdhsa_float_round_mode_16_64 0
		.amdhsa_float_denorm_mode_32 3
		.amdhsa_float_denorm_mode_16_64 3
		.amdhsa_dx10_clamp 1
		.amdhsa_ieee_mode 1
		.amdhsa_fp16_overflow 0
		.amdhsa_tg_split 0
		.amdhsa_exception_fp_ieee_invalid_op 0
		.amdhsa_exception_fp_denorm_src 0
		.amdhsa_exception_fp_ieee_div_zero 0
		.amdhsa_exception_fp_ieee_overflow 0
		.amdhsa_exception_fp_ieee_underflow 0
		.amdhsa_exception_fp_ieee_inexact 0
		.amdhsa_exception_int_div_zero 0
	.end_amdhsa_kernel

; __global__ void __launch_bounds__(512, 2) fwd_mega(Args a_) {
amdhsa.kernels:
  - .agpr_count:     0
    .args:
      - .offset:         0
        .size:           272
        .value_kind:     by_value
      - .offset:         272
        .size:           4
        .value_kind:     hidden_block_count_x
      - .offset:         276
        .size:           4
        .value_kind:     hidden_block_count_y
      - .offset:         280
        .size:           4
        .value_kind:     hidden_block_count_z
      - .offset:         284
        .size:           2
        .value_kind:     hidden_group_size_x
      - .offset:         286
        .size:           2
        .value_kind:     hidden_group_size_y
      - .offset:         288
        .size:           2
        .value_kind:     hidden_group_size_z
      - .offset:         290
        .size:           2
        .value_kind:     hidden_remainder_x
      - .offset:         292
        .size:           2
        .value_kind:     hidden_remainder_y
      - .offset:         294
        .size:           2
        .value_kind:     hidden_remainder_z
      - .offset:         312
        .size:           8
        .value_kind:     hidden_global_offset_x
      - .offset:         320
        .size:           8
        .value_kind:     hidden_global_offset_y
      - .offset:         328
        .size:           8
        .value_kind:     hidden_global_offset_z
      - .offset:         336
        .size:           2
        .value_kind:     hidden_grid_dims
      - .offset:         360
        .size:           8
        .value_kind:     hidden_multigrid_sync_arg
      - .offset:         392
        .size:           4
        .value_kind:     hidden_dynamic_lds_size
    .group_segment_fixed_size: 0
    .kernarg_segment_align: 8
    .kernarg_segment_size: 528
    .language:       OpenCL C
    .language_version:
      - 2
      - 0
    .max_flat_workgroup_size: 512
    .name:           _Z8fwd_mega4Args
    .private_segment_fixed_size: 0
    .sgpr_count:     106
    .sgpr_spill_count: 188
    .symbol:         _Z8fwd_mega4Args.kd
    .uniform_work_group_size: 1
    .uses_dynamic_stack: false
    .vgpr_count:     256
    .vgpr_spill_count: 0
    .wavefront_size: 64
